# K-loops: per-sub-phase s_setprio flips removed, one static s_setprio 1 for waves 4..7 during each K-loop
# speedup vs baseline: 1.0075x; 1.0075x over previous
.LBB0_314:
	s_add_u32 s71, s26, 0x100
	s_addc_u32 s72, s27, 0
	s_add_i32 s70, s69, 1
	s_lshl_b32 s0, s70, 2
	v_readlane_b32 s2, v253, 22
	s_add_i32 s0, s0, s2
	s_cmp_lt_i32 s0, 22
	s_cselect_b64 s[60:61], -1, 0
	s_cmp_gt_i32 s0, 21
	s_cselect_b64 s[56:57], -1, 0
	s_ashr_i32 s1, s0, 31
	s_lshl_b64 s[0:1], s[0:1], 19
	v_readlane_b32 s3, v253, 23
	s_add_u32 s2, s62, s0
	s_addc_u32 s3, s63, s1
	s_and_b64 s[0:1], s[60:61], exec
	s_cselect_b32 s27, s3, s27
	s_cselect_b32 s26, s2, s26
	s_cselect_b32 s59, s25, s35
	s_cselect_b32 s58, s24, s34
	s_add_u32 s0, s34, 0x40080
	s_addc_u32 s1, s35, 0
	v_lshl_add_u64 v[130:131], s[0:1], 0, v[180:181]
	v_lshl_add_u64 v[132:133], s[0:1], 0, v[178:179]
	s_mov_b32 s6, -2
	s_mov_b64 s[0:1], 0
	s_mov_b64 s[42:43], 0x80
	v_readfirstlane_b32 vcc_lo, v216
	s_nop 3
	s_lshr_b32 vcc_lo, vcc_lo, 6
	s_cmp_ge_u32 vcc_lo, 4
	s_cbranch_scc0 .Lprio_skip1
	s_setprio 1
.Lprio_skip1:
.LBB0_315:
	s_add_u32 s2, s34, s0
	s_addc_u32 s3, s35, s1
	s_add_u32 s2, s2, 0x100
	s_addc_u32 s3, s3, 0
	s_add_u32 s7, s71, s0
	s_addc_u32 s8, s72, s1
	s_add_i32 s9, 0, 0x10000
	s_cmpk_eq_i32 s0, 0x700
	s_cselect_b32 s5, s59, s3
	s_cselect_b32 s4, s58, s2
	v_add_u32_e32 v0, s9, v190
	s_cselect_b32 s3, s27, s8
	s_cselect_b32 s2, s26, s7
	s_add_i32 s7, 0, 0x14000
	ds_read_b128 v[134:137], v0
	ds_read_b128 v[138:141], v0 offset:1024
	ds_read_b128 v[142:145], v0 offset:2048
	ds_read_b128 v[146:149], v0 offset:3072
	v_add_u32_e32 v0, s7, v190
	ds_read_b128 v[150:153], v0
	ds_read_b128 v[154:157], v0 offset:1024
	ds_read_b128 v[158:161], v0 offset:2048
	ds_read_b128 v[162:165], v0 offset:3072
	v_lshl_add_u64 v[186:187], v[132:133], 0, s[0:1]
	s_add_i32 m0, s15, 0xc000
	ds_read_b128 v[166:169], v191
	ds_read_b128 v[182:185], v191 offset:1024
	ds_read_b128 v[192:195], v191 offset:2048
	ds_read_b128 v[196:199], v191 offset:3072
	ds_read_b128 v[200:203], v191 offset:4096
	ds_read_b128 v[204:207], v191 offset:5120
	ds_read_b128 v[208:211], v191 offset:6144
	ds_read_b128 v[212:215], v191 offset:7168
	global_load_lds_dwordx4 v[186:187], off
	v_lshl_add_u64 v[186:187], v[130:131], 0, s[0:1]
	s_add_i32 m0, s15, 0xe000
	s_nop 0
	global_load_lds_dwordx4 v[186:187], off
	s_waitcnt vmcnt(8)
	s_waitcnt lgkmcnt(0)
	s_barrier
	v_mfma_f32_16x16x32_bf16 v[126:129], v[134:137], v[166:169], v[126:129]
	v_mfma_f32_16x16x32_bf16 v[122:125], v[142:145], v[166:169], v[122:125]
	v_mfma_f32_16x16x32_bf16 v[118:121], v[134:137], v[192:195], v[118:121]
	v_mfma_f32_16x16x32_bf16 v[114:117], v[142:145], v[192:195], v[114:117]
	v_mfma_f32_16x16x32_bf16 v[110:113], v[134:137], v[200:203], v[110:113]
	v_mfma_f32_16x16x32_bf16 v[106:109], v[142:145], v[200:203], v[106:109]
	v_mfma_f32_16x16x32_bf16 v[102:105], v[134:137], v[208:211], v[102:105]
	v_mfma_f32_16x16x32_bf16 v[98:101], v[142:145], v[208:211], v[98:101]
	v_mfma_f32_16x16x32_bf16 v[126:129], v[138:141], v[182:185], v[126:129]
	v_mfma_f32_16x16x32_bf16 v[122:125], v[146:149], v[182:185], v[122:125]
	v_mfma_f32_16x16x32_bf16 v[118:121], v[138:141], v[196:199], v[118:121]
	v_mfma_f32_16x16x32_bf16 v[114:117], v[146:149], v[196:199], v[114:117]
	v_mfma_f32_16x16x32_bf16 v[110:113], v[138:141], v[204:207], v[110:113]
	v_mfma_f32_16x16x32_bf16 v[106:109], v[146:149], v[204:207], v[106:109]
	v_mfma_f32_16x16x32_bf16 v[102:105], v[138:141], v[212:215], v[102:105]
	v_mfma_f32_16x16x32_bf16 v[98:101], v[146:149], v[212:215], v[98:101]
	v_mfma_f32_16x16x32_bf16 v[94:97], v[150:153], v[166:169], v[94:97]
	v_mfma_f32_16x16x32_bf16 v[90:93], v[158:161], v[166:169], v[90:93]
	v_mfma_f32_16x16x32_bf16 v[86:89], v[150:153], v[192:195], v[86:89]
	v_mfma_f32_16x16x32_bf16 v[82:85], v[158:161], v[192:195], v[82:85]
	v_mfma_f32_16x16x32_bf16 v[78:81], v[150:153], v[200:203], v[78:81]
	v_mfma_f32_16x16x32_bf16 v[74:77], v[158:161], v[200:203], v[74:77]
	v_mfma_f32_16x16x32_bf16 v[70:73], v[150:153], v[208:211], v[70:73]
	v_mfma_f32_16x16x32_bf16 v[66:69], v[158:161], v[208:211], v[66:69]
	v_mfma_f32_16x16x32_bf16 v[94:97], v[154:157], v[182:185], v[94:97]
	v_mfma_f32_16x16x32_bf16 v[90:93], v[162:165], v[182:185], v[90:93]
	v_mfma_f32_16x16x32_bf16 v[86:89], v[154:157], v[196:199], v[86:89]
	v_mfma_f32_16x16x32_bf16 v[82:85], v[162:165], v[196:199], v[82:85]
	v_mfma_f32_16x16x32_bf16 v[78:81], v[154:157], v[204:207], v[78:81]
	v_mfma_f32_16x16x32_bf16 v[74:77], v[162:165], v[204:207], v[74:77]
	v_mfma_f32_16x16x32_bf16 v[70:73], v[154:157], v[212:215], v[70:73]
	v_mfma_f32_16x16x32_bf16 v[66:69], v[162:165], v[212:215], v[66:69]
	s_barrier
	s_add_i32 s8, s9, s14
	v_lshl_add_u64 v[186:187], s[2:3], 0, v[170:171]
	s_mov_b32 m0, s8
	ds_read_b128 v[166:169], v191 offset:16384
	ds_read_b128 v[182:185], v191 offset:17408
	ds_read_b128 v[192:195], v191 offset:18432
	ds_read_b128 v[196:199], v191 offset:19456
	ds_read_b128 v[200:203], v191 offset:20480
	ds_read_b128 v[204:207], v191 offset:21504
	ds_read_b128 v[208:211], v191 offset:22528
	ds_read_b128 v[212:215], v191 offset:23552
	global_load_lds_dwordx4 v[186:187], off
	s_add_i32 m0, s8, 0x2000
	s_add_u32 s8, s2, 0x40000
	v_lshl_add_u64 v[236:237], s[2:3], 0, v[172:173]
	s_addc_u32 s9, s3, 0
	s_add_i32 s7, s7, s14
	global_load_lds_dwordx4 v[236:237], off
	v_lshl_add_u64 v[238:239], s[8:9], 0, v[170:171]
	s_mov_b32 m0, s7
	v_lshl_add_u64 v[244:245], s[4:5], 0, v[176:177]
	global_load_lds_dwordx4 v[238:239], off
	v_lshl_add_u64 v[238:239], s[8:9], 0, v[172:173]
	s_add_i32 m0, s7, 0x2000
	s_nop 0
	global_load_lds_dwordx4 v[238:239], off
	v_lshl_add_u64 v[238:239], s[4:5], 0, v[174:175]
	s_mov_b32 m0, s15
	s_nop 0
	global_load_lds_dwordx4 v[238:239], off
	s_mov_b32 m0, s17
	s_nop 0
	global_load_lds_dwordx4 v[244:245], off
	s_waitcnt vmcnt(8)
	s_waitcnt lgkmcnt(0)
	s_barrier
	v_mfma_f32_16x16x32_bf16 v[62:65], v[134:137], v[166:169], v[62:65]
	v_mfma_f32_16x16x32_bf16 v[58:61], v[142:145], v[166:169], v[58:61]
	v_mfma_f32_16x16x32_bf16 v[54:57], v[134:137], v[192:195], v[54:57]
	v_mfma_f32_16x16x32_bf16 v[50:53], v[142:145], v[192:195], v[50:53]
	v_mfma_f32_16x16x32_bf16 v[46:49], v[134:137], v[200:203], v[46:49]
	v_mfma_f32_16x16x32_bf16 v[42:45], v[142:145], v[200:203], v[42:45]
	v_mfma_f32_16x16x32_bf16 v[38:41], v[134:137], v[208:211], v[38:41]
	v_mfma_f32_16x16x32_bf16 v[34:37], v[142:145], v[208:211], v[34:37]
	v_mfma_f32_16x16x32_bf16 v[62:65], v[138:141], v[182:185], v[62:65]
	v_mfma_f32_16x16x32_bf16 v[58:61], v[146:149], v[182:185], v[58:61]
	v_mfma_f32_16x16x32_bf16 v[54:57], v[138:141], v[196:199], v[54:57]
	v_mfma_f32_16x16x32_bf16 v[50:53], v[146:149], v[196:199], v[50:53]
	v_mfma_f32_16x16x32_bf16 v[46:49], v[138:141], v[204:207], v[46:49]
	v_mfma_f32_16x16x32_bf16 v[42:45], v[146:149], v[204:207], v[42:45]
	v_mfma_f32_16x16x32_bf16 v[38:41], v[138:141], v[212:215], v[38:41]
	v_mfma_f32_16x16x32_bf16 v[34:37], v[146:149], v[212:215], v[34:37]
	v_mfma_f32_16x16x32_bf16 v[30:33], v[150:153], v[166:169], v[30:33]
	v_mfma_f32_16x16x32_bf16 v[26:29], v[158:161], v[166:169], v[26:29]
	v_mfma_f32_16x16x32_bf16 v[22:25], v[150:153], v[192:195], v[22:25]
	v_mfma_f32_16x16x32_bf16 v[18:21], v[158:161], v[192:195], v[18:21]
	v_mfma_f32_16x16x32_bf16 v[14:17], v[150:153], v[200:203], v[14:17]
	v_mfma_f32_16x16x32_bf16 v[10:13], v[158:161], v[200:203], v[10:13]
	v_mfma_f32_16x16x32_bf16 v[6:9], v[150:153], v[208:211], v[6:9]
	v_mfma_f32_16x16x32_bf16 v[2:5], v[158:161], v[208:211], v[2:5]
	v_mfma_f32_16x16x32_bf16 v[30:33], v[154:157], v[182:185], v[30:33]
	v_mfma_f32_16x16x32_bf16 v[26:29], v[162:165], v[182:185], v[26:29]
	v_mfma_f32_16x16x32_bf16 v[22:25], v[154:157], v[196:199], v[22:25]
	v_mfma_f32_16x16x32_bf16 v[18:21], v[162:165], v[196:199], v[18:21]
	v_mfma_f32_16x16x32_bf16 v[14:17], v[154:157], v[204:207], v[14:17]
	v_mfma_f32_16x16x32_bf16 v[10:13], v[162:165], v[204:207], v[10:13]
	v_mfma_f32_16x16x32_bf16 v[6:9], v[154:157], v[212:215], v[6:9]
	v_mfma_f32_16x16x32_bf16 v[2:5], v[162:165], v[212:215], v[2:5]
	s_barrier
	s_add_i32 s7, 0, 0x18000
	v_add_u32_e32 v0, s7, v190
	s_add_i32 s8, 0, 0x1c000
	ds_read_b128 v[134:137], v0
	ds_read_b128 v[138:141], v0 offset:1024
	ds_read_b128 v[142:145], v0 offset:2048
	ds_read_b128 v[146:149], v0 offset:3072
	v_add_u32_e32 v0, s8, v190
	ds_read_b128 v[150:153], v0
	ds_read_b128 v[154:157], v0 offset:1024
	ds_read_b128 v[158:161], v0 offset:2048
	ds_read_b128 v[162:165], v0 offset:3072
	s_add_u32 s4, s4, 0x40000
	s_addc_u32 s5, s5, 0
	s_mov_b32 m0, s19
	v_lshl_add_u64 v[246:247], s[4:5], 0, v[174:175]
	ds_read_b128 v[166:169], v191 offset:32768
	ds_read_b128 v[182:185], v191 offset:33792
	ds_read_b128 v[192:195], v191 offset:34816
	ds_read_b128 v[196:199], v191 offset:35840
	ds_read_b128 v[200:203], v191 offset:36864
	ds_read_b128 v[204:207], v191 offset:37888
	ds_read_b128 v[208:211], v191 offset:38912
	ds_read_b128 v[212:215], v191 offset:39936
	global_load_lds_dwordx4 v[246:247], off
	v_lshl_add_u64 v[246:247], s[4:5], 0, v[176:177]
	s_mov_b32 m0, s40
	s_nop 0
	global_load_lds_dwordx4 v[246:247], off
	s_waitcnt vmcnt(8)
	s_waitcnt lgkmcnt(0)
	s_barrier
	v_mfma_f32_16x16x32_bf16 v[126:129], v[134:137], v[166:169], v[126:129]
	v_mfma_f32_16x16x32_bf16 v[122:125], v[142:145], v[166:169], v[122:125]
	v_mfma_f32_16x16x32_bf16 v[118:121], v[134:137], v[192:195], v[118:121]
	v_mfma_f32_16x16x32_bf16 v[114:117], v[142:145], v[192:195], v[114:117]
	v_mfma_f32_16x16x32_bf16 v[110:113], v[134:137], v[200:203], v[110:113]
	v_mfma_f32_16x16x32_bf16 v[106:109], v[142:145], v[200:203], v[106:109]
	v_mfma_f32_16x16x32_bf16 v[102:105], v[134:137], v[208:211], v[102:105]
	v_mfma_f32_16x16x32_bf16 v[98:101], v[142:145], v[208:211], v[98:101]
	v_mfma_f32_16x16x32_bf16 v[126:129], v[138:141], v[182:185], v[126:129]
	v_mfma_f32_16x16x32_bf16 v[122:125], v[146:149], v[182:185], v[122:125]
	v_mfma_f32_16x16x32_bf16 v[118:121], v[138:141], v[196:199], v[118:121]
	v_mfma_f32_16x16x32_bf16 v[114:117], v[146:149], v[196:199], v[114:117]
	v_mfma_f32_16x16x32_bf16 v[110:113], v[138:141], v[204:207], v[110:113]
	v_mfma_f32_16x16x32_bf16 v[106:109], v[146:149], v[204:207], v[106:109]
	v_mfma_f32_16x16x32_bf16 v[102:105], v[138:141], v[212:215], v[102:105]
	v_mfma_f32_16x16x32_bf16 v[98:101], v[146:149], v[212:215], v[98:101]
	v_mfma_f32_16x16x32_bf16 v[94:97], v[150:153], v[166:169], v[94:97]
	v_mfma_f32_16x16x32_bf16 v[90:93], v[158:161], v[166:169], v[90:93]
	v_mfma_f32_16x16x32_bf16 v[86:89], v[150:153], v[192:195], v[86:89]
	v_mfma_f32_16x16x32_bf16 v[82:85], v[158:161], v[192:195], v[82:85]
	v_mfma_f32_16x16x32_bf16 v[78:81], v[150:153], v[200:203], v[78:81]
	v_mfma_f32_16x16x32_bf16 v[74:77], v[158:161], v[200:203], v[74:77]
	v_mfma_f32_16x16x32_bf16 v[70:73], v[150:153], v[208:211], v[70:73]
	v_mfma_f32_16x16x32_bf16 v[66:69], v[158:161], v[208:211], v[66:69]
	v_mfma_f32_16x16x32_bf16 v[94:97], v[154:157], v[182:185], v[94:97]
	v_mfma_f32_16x16x32_bf16 v[90:93], v[162:165], v[182:185], v[90:93]
	v_mfma_f32_16x16x32_bf16 v[86:89], v[154:157], v[196:199], v[86:89]
	v_mfma_f32_16x16x32_bf16 v[82:85], v[162:165], v[196:199], v[82:85]
	v_mfma_f32_16x16x32_bf16 v[78:81], v[154:157], v[204:207], v[78:81]
	v_mfma_f32_16x16x32_bf16 v[74:77], v[162:165], v[204:207], v[74:77]
	v_mfma_f32_16x16x32_bf16 v[70:73], v[154:157], v[212:215], v[70:73]
	v_mfma_f32_16x16x32_bf16 v[66:69], v[162:165], v[212:215], v[66:69]
	s_barrier
	s_add_i32 s4, s7, s14
	v_lshl_add_u64 v[186:187], v[186:187], 0, s[42:43]
	s_mov_b32 m0, s4
	ds_read_b128 v[166:169], v191 offset:49152
	ds_read_b128 v[182:185], v191 offset:50176
	ds_read_b128 v[192:195], v191 offset:51200
	ds_read_b128 v[196:199], v191 offset:52224
	ds_read_b128 v[200:203], v191 offset:53248
	ds_read_b128 v[204:207], v191 offset:54272
	ds_read_b128 v[208:211], v191 offset:55296
	ds_read_b128 v[212:215], v191 offset:56320
	global_load_lds_dwordx4 v[186:187], off
	s_add_i32 m0, s4, 0x2000
	s_add_u32 s2, s2, 0x40080
	v_lshl_add_u64 v[186:187], v[236:237], 0, s[42:43]
	s_addc_u32 s3, s3, 0
	s_add_i32 s4, s8, s14
	global_load_lds_dwordx4 v[186:187], off
	v_lshl_add_u64 v[186:187], s[2:3], 0, v[170:171]
	s_mov_b32 m0, s4
	s_nop 0
	global_load_lds_dwordx4 v[186:187], off
	v_lshl_add_u64 v[186:187], s[2:3], 0, v[172:173]
	s_add_i32 m0, s4, 0x2000
	s_nop 0
	global_load_lds_dwordx4 v[186:187], off
	v_lshl_add_u64 v[186:187], v[238:239], 0, s[42:43]
	s_mov_b32 m0, s50
	s_nop 0
	global_load_lds_dwordx4 v[186:187], off
	v_lshl_add_u64 v[186:187], v[244:245], 0, s[42:43]
	s_mov_b32 m0, s51
	s_nop 0
	global_load_lds_dwordx4 v[186:187], off
	s_waitcnt vmcnt(8)
	s_waitcnt lgkmcnt(0)
	s_barrier
	v_mfma_f32_16x16x32_bf16 v[62:65], v[134:137], v[166:169], v[62:65]
	v_mfma_f32_16x16x32_bf16 v[58:61], v[142:145], v[166:169], v[58:61]
	v_mfma_f32_16x16x32_bf16 v[54:57], v[134:137], v[192:195], v[54:57]
	v_mfma_f32_16x16x32_bf16 v[50:53], v[142:145], v[192:195], v[50:53]
	v_mfma_f32_16x16x32_bf16 v[46:49], v[134:137], v[200:203], v[46:49]
	v_mfma_f32_16x16x32_bf16 v[42:45], v[142:145], v[200:203], v[42:45]
	v_mfma_f32_16x16x32_bf16 v[38:41], v[134:137], v[208:211], v[38:41]
	v_mfma_f32_16x16x32_bf16 v[34:37], v[142:145], v[208:211], v[34:37]
	v_mfma_f32_16x16x32_bf16 v[62:65], v[138:141], v[182:185], v[62:65]
	v_mfma_f32_16x16x32_bf16 v[58:61], v[146:149], v[182:185], v[58:61]
	v_mfma_f32_16x16x32_bf16 v[54:57], v[138:141], v[196:199], v[54:57]
	v_mfma_f32_16x16x32_bf16 v[50:53], v[146:149], v[196:199], v[50:53]
	v_mfma_f32_16x16x32_bf16 v[46:49], v[138:141], v[204:207], v[46:49]
	v_mfma_f32_16x16x32_bf16 v[42:45], v[146:149], v[204:207], v[42:45]
	v_mfma_f32_16x16x32_bf16 v[38:41], v[138:141], v[212:215], v[38:41]
	v_mfma_f32_16x16x32_bf16 v[34:37], v[146:149], v[212:215], v[34:37]
	v_mfma_f32_16x16x32_bf16 v[30:33], v[150:153], v[166:169], v[30:33]
	v_mfma_f32_16x16x32_bf16 v[26:29], v[158:161], v[166:169], v[26:29]
	v_mfma_f32_16x16x32_bf16 v[22:25], v[150:153], v[192:195], v[22:25]
	v_mfma_f32_16x16x32_bf16 v[18:21], v[158:161], v[192:195], v[18:21]
	v_mfma_f32_16x16x32_bf16 v[14:17], v[150:153], v[200:203], v[14:17]
	v_mfma_f32_16x16x32_bf16 v[10:13], v[158:161], v[200:203], v[10:13]
	v_mfma_f32_16x16x32_bf16 v[6:9], v[150:153], v[208:211], v[6:9]
	v_mfma_f32_16x16x32_bf16 v[2:5], v[158:161], v[208:211], v[2:5]
	v_mfma_f32_16x16x32_bf16 v[30:33], v[154:157], v[182:185], v[30:33]
	v_mfma_f32_16x16x32_bf16 v[26:29], v[162:165], v[182:185], v[26:29]
	v_mfma_f32_16x16x32_bf16 v[22:25], v[154:157], v[196:199], v[22:25]
	v_mfma_f32_16x16x32_bf16 v[18:21], v[162:165], v[196:199], v[18:21]
	v_mfma_f32_16x16x32_bf16 v[14:17], v[154:157], v[204:207], v[14:17]
	v_mfma_f32_16x16x32_bf16 v[10:13], v[162:165], v[204:207], v[10:13]
	v_mfma_f32_16x16x32_bf16 v[6:9], v[154:157], v[212:215], v[6:9]
	v_mfma_f32_16x16x32_bf16 v[2:5], v[162:165], v[212:215], v[2:5]
	s_barrier
	s_add_i32 s6, s6, 2
	s_add_u32 s0, s0, 0x100
	s_addc_u32 s1, s1, 0
	s_cmp_gt_u32 s6, 13
	s_cbranch_scc0 .LBB0_315
	s_setprio 0
	s_and_b64 vcc, exec, s[36:37]
	s_cbranch_vccz .LBB0_318
	s_barrier

.LBB0_349:
	s_mov_b32 s57, 2
	s_mov_b64 s[0:1], 0x100
	v_mov_b64_e32 v[2:3], v[206:207]
	v_mov_b64_e32 v[132:133], v[204:205]
	s_mov_b64 s[42:43], 0x80
	v_readfirstlane_b32 vcc_lo, v216
	s_nop 3
	s_lshr_b32 vcc_lo, vcc_lo, 6
	s_cmp_ge_u32 vcc_lo, 4
	s_cbranch_scc0 .Lprio_skip2
	s_setprio 1
.Lprio_skip2:
.LBB0_350:
	s_add_u32 s2, s34, s0
	s_addc_u32 s3, s35, s1
	s_add_u32 s58, s36, s0
	s_addc_u32 s59, s37, s1
	s_add_i32 s60, 0, 0x10000
	s_cmp_eq_u32 s53, s57
	s_cselect_b32 s5, s39, s3
	s_cselect_b32 s4, s38, s2
	v_add_u32_e32 v0, s60, v247
	s_cselect_b32 s3, s47, s59
	s_cselect_b32 s2, s46, s58
	s_add_i32 s61, 0, 0x14000
	ds_read_b128 v[134:137], v0
	ds_read_b128 v[138:141], v0 offset:1024
	ds_read_b128 v[142:145], v0 offset:2048
	ds_read_b128 v[146:149], v0 offset:3072
	v_add_u32_e32 v0, s61, v247
	ds_read_b128 v[150:153], v0
	ds_read_b128 v[154:157], v0 offset:1024
	ds_read_b128 v[158:161], v0 offset:2048
	ds_read_b128 v[162:165], v0 offset:3072
	v_lshl_add_u64 v[194:195], s[34:35], 0, v[2:3]
	s_add_i32 m0, s11, 0xc000
	ds_read_b128 v[166:169], v248
	ds_read_b128 v[170:173], v248 offset:1024
	ds_read_b128 v[174:177], v248 offset:2048
	ds_read_b128 v[178:181], v248 offset:3072
	ds_read_b128 v[182:185], v248 offset:4096
	ds_read_b128 v[186:189], v248 offset:5120
	ds_read_b128 v[190:193], v248 offset:6144
	ds_read_b128 v[208:211], v248 offset:7168
	global_load_lds_dwordx4 v[194:195], off
	v_lshl_add_u64 v[194:195], s[34:35], 0, v[132:133]
	s_add_i32 m0, s11, 0xe000
	s_nop 0
	global_load_lds_dwordx4 v[194:195], off
	s_waitcnt vmcnt(8)
	s_waitcnt lgkmcnt(0)
	s_barrier
	v_mfma_f32_16x16x32_bf16 v[128:131], v[134:137], v[166:169], v[128:131]
	v_mfma_f32_16x16x32_bf16 v[124:127], v[142:145], v[166:169], v[124:127]
	v_mfma_f32_16x16x32_bf16 v[120:123], v[134:137], v[174:177], v[120:123]
	v_mfma_f32_16x16x32_bf16 v[116:119], v[142:145], v[174:177], v[116:119]
	v_mfma_f32_16x16x32_bf16 v[112:115], v[134:137], v[182:185], v[112:115]
	v_mfma_f32_16x16x32_bf16 v[108:111], v[142:145], v[182:185], v[108:111]
	v_mfma_f32_16x16x32_bf16 v[104:107], v[134:137], v[190:193], v[104:107]
	v_mfma_f32_16x16x32_bf16 v[100:103], v[142:145], v[190:193], v[100:103]
	v_mfma_f32_16x16x32_bf16 v[128:131], v[138:141], v[170:173], v[128:131]
	v_mfma_f32_16x16x32_bf16 v[124:127], v[146:149], v[170:173], v[124:127]
	v_mfma_f32_16x16x32_bf16 v[120:123], v[138:141], v[178:181], v[120:123]
	v_mfma_f32_16x16x32_bf16 v[116:119], v[146:149], v[178:181], v[116:119]
	v_mfma_f32_16x16x32_bf16 v[112:115], v[138:141], v[186:189], v[112:115]
	v_mfma_f32_16x16x32_bf16 v[108:111], v[146:149], v[186:189], v[108:111]
	v_mfma_f32_16x16x32_bf16 v[104:107], v[138:141], v[208:211], v[104:107]
	v_mfma_f32_16x16x32_bf16 v[100:103], v[146:149], v[208:211], v[100:103]
	v_mfma_f32_16x16x32_bf16 v[96:99], v[150:153], v[166:169], v[96:99]
	v_mfma_f32_16x16x32_bf16 v[92:95], v[158:161], v[166:169], v[92:95]
	v_mfma_f32_16x16x32_bf16 v[88:91], v[150:153], v[174:177], v[88:91]
	v_mfma_f32_16x16x32_bf16 v[84:87], v[158:161], v[174:177], v[84:87]
	v_mfma_f32_16x16x32_bf16 v[80:83], v[150:153], v[182:185], v[80:83]
	v_mfma_f32_16x16x32_bf16 v[76:79], v[158:161], v[182:185], v[76:79]
	v_mfma_f32_16x16x32_bf16 v[72:75], v[150:153], v[190:193], v[72:75]
	v_mfma_f32_16x16x32_bf16 v[68:71], v[158:161], v[190:193], v[68:71]
	v_mfma_f32_16x16x32_bf16 v[96:99], v[154:157], v[170:173], v[96:99]
	v_mfma_f32_16x16x32_bf16 v[92:95], v[162:165], v[170:173], v[92:95]
	v_mfma_f32_16x16x32_bf16 v[88:91], v[154:157], v[178:181], v[88:91]
	v_mfma_f32_16x16x32_bf16 v[84:87], v[162:165], v[178:181], v[84:87]
	v_mfma_f32_16x16x32_bf16 v[80:83], v[154:157], v[186:189], v[80:83]
	v_mfma_f32_16x16x32_bf16 v[76:79], v[162:165], v[186:189], v[76:79]
	v_mfma_f32_16x16x32_bf16 v[72:75], v[154:157], v[208:211], v[72:75]
	v_mfma_f32_16x16x32_bf16 v[68:71], v[162:165], v[208:211], v[68:71]
	s_barrier
	s_add_i32 s58, s60, s10
	v_lshl_add_u64 v[194:195], s[2:3], 0, v[196:197]
	s_mov_b32 m0, s58
	ds_read_b128 v[166:169], v248 offset:16384
	ds_read_b128 v[170:173], v248 offset:17408
	ds_read_b128 v[174:177], v248 offset:18432
	ds_read_b128 v[178:181], v248 offset:19456
	ds_read_b128 v[182:185], v248 offset:20480
	ds_read_b128 v[186:189], v248 offset:21504
	ds_read_b128 v[190:193], v248 offset:22528
	ds_read_b128 v[208:211], v248 offset:23552
	global_load_lds_dwordx4 v[194:195], off
	s_add_i32 m0, s58, 0x2000
	s_add_u32 s58, s2, 0x40000
	v_lshl_add_u64 v[212:213], s[2:3], 0, v[198:199]
	s_addc_u32 s59, s3, 0
	s_add_i32 s60, s61, s10
	global_load_lds_dwordx4 v[212:213], off
	v_lshl_add_u64 v[214:215], s[58:59], 0, v[196:197]
	s_mov_b32 m0, s60
	v_lshl_add_u64 v[236:237], s[4:5], 0, v[202:203]
	global_load_lds_dwordx4 v[214:215], off
	v_lshl_add_u64 v[214:215], s[58:59], 0, v[198:199]
	s_add_i32 m0, s60, 0x2000
	s_nop 0
	global_load_lds_dwordx4 v[214:215], off
	v_lshl_add_u64 v[214:215], s[4:5], 0, v[200:201]
	s_mov_b32 m0, s11
	s_nop 0
	global_load_lds_dwordx4 v[214:215], off
	s_mov_b32 m0, s14
	s_nop 0
	global_load_lds_dwordx4 v[236:237], off
	s_waitcnt vmcnt(8)
	s_waitcnt lgkmcnt(0)
	s_barrier
	v_mfma_f32_16x16x32_bf16 v[64:67], v[134:137], v[166:169], v[64:67]
	v_mfma_f32_16x16x32_bf16 v[60:63], v[142:145], v[166:169], v[60:63]
	v_mfma_f32_16x16x32_bf16 v[56:59], v[134:137], v[174:177], v[56:59]
	v_mfma_f32_16x16x32_bf16 v[52:55], v[142:145], v[174:177], v[52:55]
	v_mfma_f32_16x16x32_bf16 v[48:51], v[134:137], v[182:185], v[48:51]
	v_mfma_f32_16x16x32_bf16 v[44:47], v[142:145], v[182:185], v[44:47]
	v_mfma_f32_16x16x32_bf16 v[40:43], v[134:137], v[190:193], v[40:43]
	v_mfma_f32_16x16x32_bf16 v[36:39], v[142:145], v[190:193], v[36:39]
	v_mfma_f32_16x16x32_bf16 v[64:67], v[138:141], v[170:173], v[64:67]
	v_mfma_f32_16x16x32_bf16 v[60:63], v[146:149], v[170:173], v[60:63]
	v_mfma_f32_16x16x32_bf16 v[56:59], v[138:141], v[178:181], v[56:59]
	v_mfma_f32_16x16x32_bf16 v[52:55], v[146:149], v[178:181], v[52:55]
	v_mfma_f32_16x16x32_bf16 v[48:51], v[138:141], v[186:189], v[48:51]
	v_mfma_f32_16x16x32_bf16 v[44:47], v[146:149], v[186:189], v[44:47]
	v_mfma_f32_16x16x32_bf16 v[40:43], v[138:141], v[208:211], v[40:43]
	v_mfma_f32_16x16x32_bf16 v[36:39], v[146:149], v[208:211], v[36:39]
	v_mfma_f32_16x16x32_bf16 v[32:35], v[150:153], v[166:169], v[32:35]
	v_mfma_f32_16x16x32_bf16 v[28:31], v[158:161], v[166:169], v[28:31]
	v_mfma_f32_16x16x32_bf16 v[24:27], v[150:153], v[174:177], v[24:27]
	v_mfma_f32_16x16x32_bf16 v[20:23], v[158:161], v[174:177], v[20:23]
	v_mfma_f32_16x16x32_bf16 v[16:19], v[150:153], v[182:185], v[16:19]
	v_mfma_f32_16x16x32_bf16 v[12:15], v[158:161], v[182:185], v[12:15]
	v_mfma_f32_16x16x32_bf16 v[8:11], v[150:153], v[190:193], v[8:11]
	v_mfma_f32_16x16x32_bf16 v[4:7], v[158:161], v[190:193], v[4:7]
	v_mfma_f32_16x16x32_bf16 v[32:35], v[154:157], v[170:173], v[32:35]
	v_mfma_f32_16x16x32_bf16 v[28:31], v[162:165], v[170:173], v[28:31]
	v_mfma_f32_16x16x32_bf16 v[24:27], v[154:157], v[178:181], v[24:27]
	v_mfma_f32_16x16x32_bf16 v[20:23], v[162:165], v[178:181], v[20:23]
	v_mfma_f32_16x16x32_bf16 v[16:19], v[154:157], v[186:189], v[16:19]
	v_mfma_f32_16x16x32_bf16 v[12:15], v[162:165], v[186:189], v[12:15]
	v_mfma_f32_16x16x32_bf16 v[8:11], v[154:157], v[208:211], v[8:11]
	v_mfma_f32_16x16x32_bf16 v[4:7], v[162:165], v[208:211], v[4:7]
	s_barrier
	s_add_i32 s58, 0, 0x18000
	v_add_u32_e32 v0, s58, v247
	s_add_i32 s59, 0, 0x1c000
	ds_read_b128 v[134:137], v0
	ds_read_b128 v[138:141], v0 offset:1024
	ds_read_b128 v[142:145], v0 offset:2048
	ds_read_b128 v[146:149], v0 offset:3072
	v_add_u32_e32 v0, s59, v247
	ds_read_b128 v[150:153], v0
	ds_read_b128 v[154:157], v0 offset:1024
	ds_read_b128 v[158:161], v0 offset:2048
	ds_read_b128 v[162:165], v0 offset:3072
	s_add_u32 s4, s4, 0x40000
	s_addc_u32 s5, s5, 0
	s_mov_b32 m0, s15
	v_lshl_add_u64 v[238:239], s[4:5], 0, v[200:201]
	ds_read_b128 v[166:169], v248 offset:32768
	ds_read_b128 v[170:173], v248 offset:33792
	ds_read_b128 v[174:177], v248 offset:34816
	ds_read_b128 v[178:181], v248 offset:35840
	ds_read_b128 v[182:185], v248 offset:36864
	ds_read_b128 v[186:189], v248 offset:37888
	ds_read_b128 v[190:193], v248 offset:38912
	ds_read_b128 v[208:211], v248 offset:39936
	global_load_lds_dwordx4 v[238:239], off
	v_lshl_add_u64 v[238:239], s[4:5], 0, v[202:203]
	s_mov_b32 m0, s17
	s_nop 0
	global_load_lds_dwordx4 v[238:239], off
	s_waitcnt vmcnt(8)
	s_waitcnt lgkmcnt(0)
	s_barrier
	v_mfma_f32_16x16x32_bf16 v[128:131], v[134:137], v[166:169], v[128:131]
	v_mfma_f32_16x16x32_bf16 v[124:127], v[142:145], v[166:169], v[124:127]
	v_mfma_f32_16x16x32_bf16 v[120:123], v[134:137], v[174:177], v[120:123]
	v_mfma_f32_16x16x32_bf16 v[116:119], v[142:145], v[174:177], v[116:119]
	v_mfma_f32_16x16x32_bf16 v[112:115], v[134:137], v[182:185], v[112:115]
	v_mfma_f32_16x16x32_bf16 v[108:111], v[142:145], v[182:185], v[108:111]
	v_mfma_f32_16x16x32_bf16 v[104:107], v[134:137], v[190:193], v[104:107]
	v_mfma_f32_16x16x32_bf16 v[100:103], v[142:145], v[190:193], v[100:103]
	v_mfma_f32_16x16x32_bf16 v[128:131], v[138:141], v[170:173], v[128:131]
	v_mfma_f32_16x16x32_bf16 v[124:127], v[146:149], v[170:173], v[124:127]
	v_mfma_f32_16x16x32_bf16 v[120:123], v[138:141], v[178:181], v[120:123]
	v_mfma_f32_16x16x32_bf16 v[116:119], v[146:149], v[178:181], v[116:119]
	v_mfma_f32_16x16x32_bf16 v[112:115], v[138:141], v[186:189], v[112:115]
	v_mfma_f32_16x16x32_bf16 v[108:111], v[146:149], v[186:189], v[108:111]
	v_mfma_f32_16x16x32_bf16 v[104:107], v[138:141], v[208:211], v[104:107]
	v_mfma_f32_16x16x32_bf16 v[100:103], v[146:149], v[208:211], v[100:103]
	v_mfma_f32_16x16x32_bf16 v[96:99], v[150:153], v[166:169], v[96:99]
	v_mfma_f32_16x16x32_bf16 v[92:95], v[158:161], v[166:169], v[92:95]
	v_mfma_f32_16x16x32_bf16 v[88:91], v[150:153], v[174:177], v[88:91]
	v_mfma_f32_16x16x32_bf16 v[84:87], v[158:161], v[174:177], v[84:87]
	v_mfma_f32_16x16x32_bf16 v[80:83], v[150:153], v[182:185], v[80:83]
	v_mfma_f32_16x16x32_bf16 v[76:79], v[158:161], v[182:185], v[76:79]
	v_mfma_f32_16x16x32_bf16 v[72:75], v[150:153], v[190:193], v[72:75]
	v_mfma_f32_16x16x32_bf16 v[68:71], v[158:161], v[190:193], v[68:71]
	v_mfma_f32_16x16x32_bf16 v[96:99], v[154:157], v[170:173], v[96:99]
	v_mfma_f32_16x16x32_bf16 v[92:95], v[162:165], v[170:173], v[92:95]
	v_mfma_f32_16x16x32_bf16 v[88:91], v[154:157], v[178:181], v[88:91]
	v_mfma_f32_16x16x32_bf16 v[84:87], v[162:165], v[178:181], v[84:87]
	v_mfma_f32_16x16x32_bf16 v[80:83], v[154:157], v[186:189], v[80:83]
	v_mfma_f32_16x16x32_bf16 v[76:79], v[162:165], v[186:189], v[76:79]
	v_mfma_f32_16x16x32_bf16 v[72:75], v[154:157], v[208:211], v[72:75]
	v_mfma_f32_16x16x32_bf16 v[68:71], v[162:165], v[208:211], v[68:71]
	s_barrier
	s_add_i32 s4, s58, s10
	v_lshl_add_u64 v[194:195], v[194:195], 0, s[42:43]
	s_mov_b32 m0, s4
	ds_read_b128 v[166:169], v248 offset:49152
	ds_read_b128 v[170:173], v248 offset:50176
	ds_read_b128 v[174:177], v248 offset:51200
	ds_read_b128 v[178:181], v248 offset:52224
	ds_read_b128 v[182:185], v248 offset:53248
	ds_read_b128 v[186:189], v248 offset:54272
	ds_read_b128 v[190:193], v248 offset:55296
	ds_read_b128 v[208:211], v248 offset:56320
	global_load_lds_dwordx4 v[194:195], off
	s_add_i32 m0, s4, 0x2000
	s_add_u32 s2, s2, 0x40080
	v_lshl_add_u64 v[194:195], v[212:213], 0, s[42:43]
	s_addc_u32 s3, s3, 0
	s_add_i32 s4, s59, s10
	global_load_lds_dwordx4 v[194:195], off
	v_lshl_add_u64 v[194:195], s[2:3], 0, v[196:197]
	s_mov_b32 m0, s4
	s_nop 0
	global_load_lds_dwordx4 v[194:195], off
	v_lshl_add_u64 v[194:195], s[2:3], 0, v[198:199]
	s_add_i32 m0, s4, 0x2000
	s_nop 0
	global_load_lds_dwordx4 v[194:195], off
	v_lshl_add_u64 v[194:195], v[214:215], 0, s[42:43]
	s_mov_b32 m0, s41
	s_nop 0
	global_load_lds_dwordx4 v[194:195], off
	v_lshl_add_u64 v[194:195], v[236:237], 0, s[42:43]
	s_mov_b32 m0, s44
	s_nop 0
	global_load_lds_dwordx4 v[194:195], off
	s_waitcnt vmcnt(8)
	s_waitcnt lgkmcnt(0)
	s_barrier
	v_mfma_f32_16x16x32_bf16 v[64:67], v[134:137], v[166:169], v[64:67]
	v_mfma_f32_16x16x32_bf16 v[60:63], v[142:145], v[166:169], v[60:63]
	v_mfma_f32_16x16x32_bf16 v[56:59], v[134:137], v[174:177], v[56:59]
	v_mfma_f32_16x16x32_bf16 v[52:55], v[142:145], v[174:177], v[52:55]
	v_mfma_f32_16x16x32_bf16 v[48:51], v[134:137], v[182:185], v[48:51]
	v_mfma_f32_16x16x32_bf16 v[44:47], v[142:145], v[182:185], v[44:47]
	v_mfma_f32_16x16x32_bf16 v[40:43], v[134:137], v[190:193], v[40:43]
	v_mfma_f32_16x16x32_bf16 v[36:39], v[142:145], v[190:193], v[36:39]
	v_mfma_f32_16x16x32_bf16 v[64:67], v[138:141], v[170:173], v[64:67]
	v_mfma_f32_16x16x32_bf16 v[60:63], v[146:149], v[170:173], v[60:63]
	v_mfma_f32_16x16x32_bf16 v[56:59], v[138:141], v[178:181], v[56:59]
	v_mfma_f32_16x16x32_bf16 v[52:55], v[146:149], v[178:181], v[52:55]
	v_mfma_f32_16x16x32_bf16 v[48:51], v[138:141], v[186:189], v[48:51]
	v_mfma_f32_16x16x32_bf16 v[44:47], v[146:149], v[186:189], v[44:47]
	v_mfma_f32_16x16x32_bf16 v[40:43], v[138:141], v[208:211], v[40:43]
	v_mfma_f32_16x16x32_bf16 v[36:39], v[146:149], v[208:211], v[36:39]
	v_mfma_f32_16x16x32_bf16 v[32:35], v[150:153], v[166:169], v[32:35]
	v_mfma_f32_16x16x32_bf16 v[28:31], v[158:161], v[166:169], v[28:31]
	v_mfma_f32_16x16x32_bf16 v[24:27], v[150:153], v[174:177], v[24:27]
	v_mfma_f32_16x16x32_bf16 v[20:23], v[158:161], v[174:177], v[20:23]
	v_mfma_f32_16x16x32_bf16 v[16:19], v[150:153], v[182:185], v[16:19]
	v_mfma_f32_16x16x32_bf16 v[12:15], v[158:161], v[182:185], v[12:15]
	v_mfma_f32_16x16x32_bf16 v[8:11], v[150:153], v[190:193], v[8:11]
	v_mfma_f32_16x16x32_bf16 v[4:7], v[158:161], v[190:193], v[4:7]
	v_mfma_f32_16x16x32_bf16 v[32:35], v[154:157], v[170:173], v[32:35]
	v_mfma_f32_16x16x32_bf16 v[28:31], v[162:165], v[170:173], v[28:31]
	v_mfma_f32_16x16x32_bf16 v[24:27], v[154:157], v[178:181], v[24:27]
	v_mfma_f32_16x16x32_bf16 v[20:23], v[162:165], v[178:181], v[20:23]
	v_mfma_f32_16x16x32_bf16 v[16:19], v[154:157], v[186:189], v[16:19]
	v_mfma_f32_16x16x32_bf16 v[12:15], v[162:165], v[186:189], v[12:15]
	v_mfma_f32_16x16x32_bf16 v[8:11], v[154:157], v[208:211], v[8:11]
	v_mfma_f32_16x16x32_bf16 v[4:7], v[162:165], v[208:211], v[4:7]
	s_barrier
	s_add_i32 s2, s57, 2
	s_add_u32 s0, s0, 0x100
	s_addc_u32 s1, s1, 0
	v_lshl_add_u64 v[132:133], v[132:133], 0, s[62:63]
	v_lshl_add_u64 v[2:3], v[2:3], 0, s[62:63]
	s_cmp_ge_i32 s57, s53
	s_mov_b32 s57, s2
	s_cbranch_scc0 .LBB0_350
	s_setprio 0
	s_and_b64 vcc, exec, s[26:27]
	s_cbranch_vccz .LBB0_353
	s_barrier

.LBB0_571:
	s_cmp_lt_i32 s54, 1
	s_cbranch_scc1 .LBB0_574
	v_mad_u64_u32 v[132:133], s[0:1], s55, v185, v[184:185]
	v_readlane_b32 s0, v252, 39
	s_add_i32 s4, s54, -2
	v_readlane_b32 s1, v252, 40
	s_lshl_b32 s8, s55, 7
	s_mov_b32 s9, s1
	s_add_u32 s5, s28, 0x100
	v_mad_u64_u32 v[2:3], s[2:3], v213, s55, v[186:187]
	s_addc_u32 s6, s29, 0
	s_mov_b32 s3, s9
	s_add_u32 s0, s26, 0x80
	v_mov_b32_e32 v3, v1
	v_mov_b32_e32 v133, v1
	v_writelane_b32 v252, s2, 39
	s_addc_u32 s1, s27, 0
	v_lshl_add_u64 v[2:3], s[8:9], 0, v[2:3]
	v_writelane_b32 v252, s3, 40
	v_lshl_add_u64 v[132:133], s[8:9], 0, v[132:133]
	s_mov_b32 s2, 0
	v_readfirstlane_b32 vcc_lo, v216
	s_nop 3
	s_lshr_b32 vcc_lo, vcc_lo, 6
	s_cmp_ge_u32 vcc_lo, 4
	s_cbranch_scc0 .Lprio_skip3
	s_setprio 1
.Lprio_skip3:
.LBB0_573:
	s_add_i32 s7, s2, 2
	s_add_u32 s8, s0, 0x80
	s_addc_u32 s3, s1, 0
	s_add_i32 s9, 0, 0x10000
	s_add_i32 s80, 0, 0x14000
	v_add_u32_e32 v0, s9, v212
	ds_read_b128 v[134:137], v0
	ds_read_b128 v[138:141], v0 offset:1024
	ds_read_b128 v[142:145], v0 offset:2048
	ds_read_b128 v[146:149], v0 offset:3072
	v_add_u32_e32 v0, s80, v212
	ds_read_b128 v[150:153], v0
	ds_read_b128 v[154:157], v0 offset:1024
	ds_read_b128 v[158:161], v0 offset:2048
	ds_read_b128 v[162:165], v0 offset:3072
	s_cmp_eq_u32 s4, s2
	s_cselect_b32 s2, s78, s8
	s_cselect_b32 s3, s79, s3
	s_cselect_b32 s8, s15, s55
	s_cselect_b32 s39, s77, s6
	s_cselect_b32 s38, s76, s5
	s_cselect_b32 s81, s17, s14
	v_lshl_add_u64 v[182:183], s[0:1], 0, v[132:133]
	s_add_i32 m0, s53, 0xc000
	ds_read_b128 v[166:169], v214
	ds_read_b128 v[170:173], v214 offset:1024
	ds_read_b128 v[174:177], v214 offset:2048
	ds_read_b128 v[178:181], v214 offset:3072
	ds_read_b128 v[188:191], v214 offset:4096
	ds_read_b128 v[192:195], v214 offset:5120
	ds_read_b128 v[196:199], v214 offset:6144
	ds_read_b128 v[200:203], v214 offset:7168
	global_load_lds_dwordx4 v[182:183], off
	v_lshl_add_u64 v[182:183], s[0:1], 0, v[2:3]
	s_add_i32 m0, s53, 0xe000
	s_nop 0
	global_load_lds_dwordx4 v[182:183], off
	s_waitcnt vmcnt(8)
	s_waitcnt lgkmcnt(0)
	s_barrier
	v_mfma_f32_16x16x32_bf16 v[128:131], v[134:137], v[166:169], v[128:131]
	v_mfma_f32_16x16x32_bf16 v[124:127], v[142:145], v[166:169], v[124:127]
	v_mfma_f32_16x16x32_bf16 v[120:123], v[134:137], v[174:177], v[120:123]
	v_mfma_f32_16x16x32_bf16 v[116:119], v[142:145], v[174:177], v[116:119]
	v_mfma_f32_16x16x32_bf16 v[112:115], v[134:137], v[188:191], v[112:115]
	v_mfma_f32_16x16x32_bf16 v[108:111], v[142:145], v[188:191], v[108:111]
	v_mfma_f32_16x16x32_bf16 v[104:107], v[134:137], v[196:199], v[104:107]
	v_mfma_f32_16x16x32_bf16 v[100:103], v[142:145], v[196:199], v[100:103]
	v_mfma_f32_16x16x32_bf16 v[128:131], v[138:141], v[170:173], v[128:131]
	v_mfma_f32_16x16x32_bf16 v[124:127], v[146:149], v[170:173], v[124:127]
	v_mfma_f32_16x16x32_bf16 v[120:123], v[138:141], v[178:181], v[120:123]
	v_mfma_f32_16x16x32_bf16 v[116:119], v[146:149], v[178:181], v[116:119]
	v_mfma_f32_16x16x32_bf16 v[112:115], v[138:141], v[192:195], v[112:115]
	v_mfma_f32_16x16x32_bf16 v[108:111], v[146:149], v[192:195], v[108:111]
	v_mfma_f32_16x16x32_bf16 v[104:107], v[138:141], v[200:203], v[104:107]
	v_mfma_f32_16x16x32_bf16 v[100:103], v[146:149], v[200:203], v[100:103]
	v_mfma_f32_16x16x32_bf16 v[96:99], v[150:153], v[166:169], v[96:99]
	v_mfma_f32_16x16x32_bf16 v[92:95], v[158:161], v[166:169], v[92:95]
	v_mfma_f32_16x16x32_bf16 v[88:91], v[150:153], v[174:177], v[88:91]
	v_mfma_f32_16x16x32_bf16 v[84:87], v[158:161], v[174:177], v[84:87]
	v_mfma_f32_16x16x32_bf16 v[80:83], v[150:153], v[188:191], v[80:83]
	v_mfma_f32_16x16x32_bf16 v[76:79], v[158:161], v[188:191], v[76:79]
	v_mfma_f32_16x16x32_bf16 v[72:75], v[150:153], v[196:199], v[72:75]
	v_mfma_f32_16x16x32_bf16 v[68:71], v[158:161], v[196:199], v[68:71]
	v_mfma_f32_16x16x32_bf16 v[96:99], v[154:157], v[170:173], v[96:99]
	v_mfma_f32_16x16x32_bf16 v[92:95], v[162:165], v[170:173], v[92:95]
	v_mfma_f32_16x16x32_bf16 v[88:91], v[154:157], v[178:181], v[88:91]
	v_mfma_f32_16x16x32_bf16 v[84:87], v[162:165], v[178:181], v[84:87]
	v_mfma_f32_16x16x32_bf16 v[80:83], v[154:157], v[192:195], v[80:83]
	v_mfma_f32_16x16x32_bf16 v[76:79], v[162:165], v[192:195], v[76:79]
	v_mfma_f32_16x16x32_bf16 v[72:75], v[154:157], v[200:203], v[72:75]
	v_mfma_f32_16x16x32_bf16 v[68:71], v[162:165], v[200:203], v[68:71]
	s_barrier
	s_add_i32 s9, s9, s52
	v_mad_u64_u32 v[182:183], s[46:47], s81, v187, v[184:185]
	s_mov_b32 m0, s9
	ds_read_b128 v[166:169], v214 offset:16384
	ds_read_b128 v[170:173], v214 offset:17408
	ds_read_b128 v[174:177], v214 offset:18432
	ds_read_b128 v[178:181], v214 offset:19456
	ds_read_b128 v[188:191], v214 offset:20480
	ds_read_b128 v[192:195], v214 offset:21504
	ds_read_b128 v[196:199], v214 offset:22528
	ds_read_b128 v[200:203], v214 offset:23552
	v_mov_b32_e32 v183, v1
	global_load_lds_dwordx4 v182, s[38:39]
	v_lshl_add_u32 v0, s81, 6, v182
	s_add_i32 m0, s9, 0x2000
	s_lshl_b32 s9, s81, 7
	v_lshl_add_u64 v[204:205], s[38:39], 0, v[182:183]
	v_lshl_add_u64 v[206:207], s[38:39], 0, v[0:1]
	global_load_lds_dwordx4 v0, s[38:39]
	s_add_u32 s38, s38, s9
	s_addc_u32 s39, s39, 0
	s_add_i32 s9, s80, s52
	s_mov_b32 m0, s9
	v_lshl_add_u64 v[208:209], s[38:39], 0, v[182:183]
	global_load_lds_dwordx4 v182, s[38:39]
	s_add_i32 m0, s9, 0x2000
	v_lshl_add_u64 v[182:183], s[38:39], 0, v[0:1]
	global_load_lds_dwordx4 v0, s[38:39]
	v_mad_u64_u32 v[236:237], s[38:39], s8, v185, v[184:185]
	s_mov_b32 m0, s53
	v_lshl_add_u32 v0, s8, 6, v236
	global_load_lds_dwordx4 v236, s[2:3]
	s_mov_b32 m0, s24
	v_mov_b32_e32 v237, v1
	global_load_lds_dwordx4 v0, s[2:3]
	s_waitcnt vmcnt(8)
	s_waitcnt lgkmcnt(0)
	v_lshl_add_u64 v[238:239], s[2:3], 0, v[236:237]
	v_lshl_add_u64 v[244:245], s[2:3], 0, v[0:1]
	s_barrier
	v_mfma_f32_16x16x32_bf16 v[64:67], v[134:137], v[166:169], v[64:67]
	v_mfma_f32_16x16x32_bf16 v[60:63], v[142:145], v[166:169], v[60:63]
	v_mfma_f32_16x16x32_bf16 v[56:59], v[134:137], v[174:177], v[56:59]
	v_mfma_f32_16x16x32_bf16 v[52:55], v[142:145], v[174:177], v[52:55]
	v_mfma_f32_16x16x32_bf16 v[48:51], v[134:137], v[188:191], v[48:51]
	v_mfma_f32_16x16x32_bf16 v[44:47], v[142:145], v[188:191], v[44:47]
	v_mfma_f32_16x16x32_bf16 v[40:43], v[134:137], v[196:199], v[40:43]
	v_mfma_f32_16x16x32_bf16 v[36:39], v[142:145], v[196:199], v[36:39]
	v_mfma_f32_16x16x32_bf16 v[64:67], v[138:141], v[170:173], v[64:67]
	v_mfma_f32_16x16x32_bf16 v[60:63], v[146:149], v[170:173], v[60:63]
	v_mfma_f32_16x16x32_bf16 v[56:59], v[138:141], v[178:181], v[56:59]
	v_mfma_f32_16x16x32_bf16 v[52:55], v[146:149], v[178:181], v[52:55]
	v_mfma_f32_16x16x32_bf16 v[48:51], v[138:141], v[192:195], v[48:51]
	v_mfma_f32_16x16x32_bf16 v[44:47], v[146:149], v[192:195], v[44:47]
	v_mfma_f32_16x16x32_bf16 v[40:43], v[138:141], v[200:203], v[40:43]
	v_mfma_f32_16x16x32_bf16 v[36:39], v[146:149], v[200:203], v[36:39]
	v_mfma_f32_16x16x32_bf16 v[32:35], v[150:153], v[166:169], v[32:35]
	v_mfma_f32_16x16x32_bf16 v[28:31], v[158:161], v[166:169], v[28:31]
	v_mfma_f32_16x16x32_bf16 v[24:27], v[150:153], v[174:177], v[24:27]
	v_mfma_f32_16x16x32_bf16 v[20:23], v[158:161], v[174:177], v[20:23]
	v_mfma_f32_16x16x32_bf16 v[16:19], v[150:153], v[188:191], v[16:19]
	v_mfma_f32_16x16x32_bf16 v[12:15], v[158:161], v[188:191], v[12:15]
	v_mfma_f32_16x16x32_bf16 v[8:11], v[150:153], v[196:199], v[8:11]
	v_mfma_f32_16x16x32_bf16 v[4:7], v[158:161], v[196:199], v[4:7]
	v_mfma_f32_16x16x32_bf16 v[32:35], v[154:157], v[170:173], v[32:35]
	v_mfma_f32_16x16x32_bf16 v[28:31], v[162:165], v[170:173], v[28:31]
	v_mfma_f32_16x16x32_bf16 v[24:27], v[154:157], v[178:181], v[24:27]
	v_mfma_f32_16x16x32_bf16 v[20:23], v[162:165], v[178:181], v[20:23]
	v_mfma_f32_16x16x32_bf16 v[16:19], v[154:157], v[192:195], v[16:19]
	v_mfma_f32_16x16x32_bf16 v[12:15], v[162:165], v[192:195], v[12:15]
	v_mfma_f32_16x16x32_bf16 v[8:11], v[154:157], v[200:203], v[8:11]
	v_mfma_f32_16x16x32_bf16 v[4:7], v[162:165], v[200:203], v[4:7]
	s_barrier
	s_add_i32 s9, 0, 0x18000
	s_add_i32 s38, 0, 0x1c000
	v_add_u32_e32 v146, s9, v212
	v_add_u32_e32 v162, s38, v212
	ds_read_b128 v[134:137], v146
	ds_read_b128 v[138:141], v146 offset:1024
	ds_read_b128 v[142:145], v146 offset:2048
	ds_read_b128 v[146:149], v146 offset:3072
	ds_read_b128 v[150:153], v162
	ds_read_b128 v[154:157], v162 offset:1024
	ds_read_b128 v[158:161], v162 offset:2048
	ds_read_b128 v[162:165], v162 offset:3072
	s_lshl_b32 s8, s8, 7
	s_add_u32 s2, s2, s8
	s_addc_u32 s3, s3, 0
	s_mov_b32 m0, s25
	ds_read_b128 v[166:169], v214 offset:32768
	ds_read_b128 v[170:173], v214 offset:33792
	ds_read_b128 v[174:177], v214 offset:34816
	ds_read_b128 v[178:181], v214 offset:35840
	ds_read_b128 v[188:191], v214 offset:36864
	ds_read_b128 v[192:195], v214 offset:37888
	ds_read_b128 v[196:199], v214 offset:38912
	ds_read_b128 v[200:203], v214 offset:39936
	global_load_lds_dwordx4 v236, s[2:3]
	s_mov_b32 m0, s48
	s_nop 0
	global_load_lds_dwordx4 v0, s[2:3]
	s_waitcnt vmcnt(8)
	s_waitcnt lgkmcnt(0)
	s_barrier
	v_mfma_f32_16x16x32_bf16 v[128:131], v[134:137], v[166:169], v[128:131]
	v_mfma_f32_16x16x32_bf16 v[124:127], v[142:145], v[166:169], v[124:127]
	v_mfma_f32_16x16x32_bf16 v[120:123], v[134:137], v[174:177], v[120:123]
	v_mfma_f32_16x16x32_bf16 v[116:119], v[142:145], v[174:177], v[116:119]
	v_mfma_f32_16x16x32_bf16 v[112:115], v[134:137], v[188:191], v[112:115]
	v_mfma_f32_16x16x32_bf16 v[108:111], v[142:145], v[188:191], v[108:111]
	v_mfma_f32_16x16x32_bf16 v[104:107], v[134:137], v[196:199], v[104:107]
	v_mfma_f32_16x16x32_bf16 v[100:103], v[142:145], v[196:199], v[100:103]
	v_mfma_f32_16x16x32_bf16 v[128:131], v[138:141], v[170:173], v[128:131]
	v_mfma_f32_16x16x32_bf16 v[124:127], v[146:149], v[170:173], v[124:127]
	v_mfma_f32_16x16x32_bf16 v[120:123], v[138:141], v[178:181], v[120:123]
	v_mfma_f32_16x16x32_bf16 v[116:119], v[146:149], v[178:181], v[116:119]
	v_mfma_f32_16x16x32_bf16 v[112:115], v[138:141], v[192:195], v[112:115]
	v_mfma_f32_16x16x32_bf16 v[108:111], v[146:149], v[192:195], v[108:111]
	v_mfma_f32_16x16x32_bf16 v[104:107], v[138:141], v[200:203], v[104:107]
	v_mfma_f32_16x16x32_bf16 v[100:103], v[146:149], v[200:203], v[100:103]
	v_mfma_f32_16x16x32_bf16 v[96:99], v[150:153], v[166:169], v[96:99]
	v_mfma_f32_16x16x32_bf16 v[92:95], v[158:161], v[166:169], v[92:95]
	v_mfma_f32_16x16x32_bf16 v[88:91], v[150:153], v[174:177], v[88:91]
	v_mfma_f32_16x16x32_bf16 v[84:87], v[158:161], v[174:177], v[84:87]
	v_mfma_f32_16x16x32_bf16 v[80:83], v[150:153], v[188:191], v[80:83]
	v_mfma_f32_16x16x32_bf16 v[76:79], v[158:161], v[188:191], v[76:79]
	v_mfma_f32_16x16x32_bf16 v[72:75], v[150:153], v[196:199], v[72:75]
	v_mfma_f32_16x16x32_bf16 v[68:71], v[158:161], v[196:199], v[68:71]
	v_mfma_f32_16x16x32_bf16 v[96:99], v[154:157], v[170:173], v[96:99]
	v_mfma_f32_16x16x32_bf16 v[92:95], v[162:165], v[170:173], v[92:95]
	v_mfma_f32_16x16x32_bf16 v[88:91], v[154:157], v[178:181], v[88:91]
	v_mfma_f32_16x16x32_bf16 v[84:87], v[162:165], v[178:181], v[84:87]
	v_mfma_f32_16x16x32_bf16 v[80:83], v[154:157], v[192:195], v[80:83]
	v_mfma_f32_16x16x32_bf16 v[76:79], v[162:165], v[192:195], v[76:79]
	v_mfma_f32_16x16x32_bf16 v[72:75], v[154:157], v[200:203], v[72:75]
	v_mfma_f32_16x16x32_bf16 v[68:71], v[162:165], v[200:203], v[68:71]
	s_barrier
	s_add_i32 s2, s9, s52
	v_lshl_add_u64 v[204:205], v[204:205], 0, s[42:43]
	s_mov_b32 m0, s2
	ds_read_b128 v[166:169], v214 offset:49152
	ds_read_b128 v[170:173], v214 offset:50176
	ds_read_b128 v[174:177], v214 offset:51200
	ds_read_b128 v[178:181], v214 offset:52224
	ds_read_b128 v[188:191], v214 offset:53248
	ds_read_b128 v[192:195], v214 offset:54272
	ds_read_b128 v[196:199], v214 offset:55296
	ds_read_b128 v[200:203], v214 offset:56320
	global_load_lds_dwordx4 v[204:205], off
	v_lshl_add_u64 v[204:205], v[206:207], 0, s[42:43]
	s_add_i32 m0, s2, 0x2000
	s_add_i32 s2, s38, s52
	global_load_lds_dwordx4 v[204:205], off
	v_lshl_add_u64 v[204:205], v[208:209], 0, s[42:43]
	s_mov_b32 m0, s2
	v_lshl_add_u64 v[182:183], v[182:183], 0, s[42:43]
	global_load_lds_dwordx4 v[204:205], off
	s_add_i32 m0, s2, 0x2000
	s_nop 0
	global_load_lds_dwordx4 v[182:183], off
	v_lshl_add_u64 v[182:183], v[238:239], 0, s[42:43]
	s_mov_b32 m0, s59
	s_nop 0
	global_load_lds_dwordx4 v[182:183], off
	v_lshl_add_u64 v[182:183], v[244:245], 0, s[42:43]
	s_mov_b32 m0, s56
	s_nop 0
	global_load_lds_dwordx4 v[182:183], off
	s_waitcnt vmcnt(8)
	s_waitcnt lgkmcnt(0)
	s_barrier
	v_mfma_f32_16x16x32_bf16 v[64:67], v[134:137], v[166:169], v[64:67]
	v_mfma_f32_16x16x32_bf16 v[60:63], v[142:145], v[166:169], v[60:63]
	v_mfma_f32_16x16x32_bf16 v[56:59], v[134:137], v[174:177], v[56:59]
	v_mfma_f32_16x16x32_bf16 v[52:55], v[142:145], v[174:177], v[52:55]
	v_mfma_f32_16x16x32_bf16 v[48:51], v[134:137], v[188:191], v[48:51]
	v_mfma_f32_16x16x32_bf16 v[44:47], v[142:145], v[188:191], v[44:47]
	v_mfma_f32_16x16x32_bf16 v[40:43], v[134:137], v[196:199], v[40:43]
	v_mfma_f32_16x16x32_bf16 v[36:39], v[142:145], v[196:199], v[36:39]
	v_mfma_f32_16x16x32_bf16 v[64:67], v[138:141], v[170:173], v[64:67]
	v_mfma_f32_16x16x32_bf16 v[60:63], v[146:149], v[170:173], v[60:63]
	v_mfma_f32_16x16x32_bf16 v[56:59], v[138:141], v[178:181], v[56:59]
	v_mfma_f32_16x16x32_bf16 v[52:55], v[146:149], v[178:181], v[52:55]
	v_mfma_f32_16x16x32_bf16 v[48:51], v[138:141], v[192:195], v[48:51]
	v_mfma_f32_16x16x32_bf16 v[44:47], v[146:149], v[192:195], v[44:47]
	v_mfma_f32_16x16x32_bf16 v[40:43], v[138:141], v[200:203], v[40:43]
	v_mfma_f32_16x16x32_bf16 v[36:39], v[146:149], v[200:203], v[36:39]
	v_mfma_f32_16x16x32_bf16 v[32:35], v[150:153], v[166:169], v[32:35]
	v_mfma_f32_16x16x32_bf16 v[28:31], v[158:161], v[166:169], v[28:31]
	v_mfma_f32_16x16x32_bf16 v[24:27], v[150:153], v[174:177], v[24:27]
	v_mfma_f32_16x16x32_bf16 v[20:23], v[158:161], v[174:177], v[20:23]
	v_mfma_f32_16x16x32_bf16 v[16:19], v[150:153], v[188:191], v[16:19]
	v_mfma_f32_16x16x32_bf16 v[12:15], v[158:161], v[188:191], v[12:15]
	v_mfma_f32_16x16x32_bf16 v[8:11], v[150:153], v[196:199], v[8:11]
	v_mfma_f32_16x16x32_bf16 v[4:7], v[158:161], v[196:199], v[4:7]
	v_mfma_f32_16x16x32_bf16 v[32:35], v[154:157], v[170:173], v[32:35]
	v_mfma_f32_16x16x32_bf16 v[28:31], v[162:165], v[170:173], v[28:31]
	v_mfma_f32_16x16x32_bf16 v[24:27], v[154:157], v[178:181], v[24:27]
	v_mfma_f32_16x16x32_bf16 v[20:23], v[162:165], v[178:181], v[20:23]
	v_mfma_f32_16x16x32_bf16 v[16:19], v[154:157], v[192:195], v[16:19]
	v_mfma_f32_16x16x32_bf16 v[12:15], v[162:165], v[192:195], v[12:15]
	v_mfma_f32_16x16x32_bf16 v[8:11], v[154:157], v[200:203], v[8:11]
	v_mfma_f32_16x16x32_bf16 v[4:7], v[162:165], v[200:203], v[4:7]
	s_barrier
	s_add_u32 s5, s5, 0x100
	s_addc_u32 s6, s6, 0
	s_add_u32 s0, s0, 0x100
	s_addc_u32 s1, s1, 0
	s_cmp_ge_i32 s7, s54
	s_mov_b32 s2, s7
	s_cbranch_scc0 .LBB0_573
	s_setprio 0

.LBB0_911:
	s_cmp_lt_i32 s44, 1
	s_cbranch_scc1 .LBB0_914
	v_mad_u64_u32 v[136:137], s[62:63], s17, v133, v[132:133]
	v_readlane_b32 s62, v252, 39
	s_add_i32 s10, s44, -2
	v_readlane_b32 s63, v252, 40
	s_lshl_b32 s66, s17, 7
	s_mov_b32 s67, s63
	s_add_u32 s11, s6, 0x100
	s_addc_u32 s15, s7, 0
	v_mad_u64_u32 v[2:3], s[64:65], v141, s17, v[134:135]
	s_mov_b32 s35, s67
	s_add_u32 s62, s4, 0x80
	v_mov_b32_e32 v3, v1
	v_mov_b32_e32 v137, v1
	v_writelane_b32 v252, s34, 39
	s_addc_u32 s63, s5, 0
	v_lshl_add_u64 v[2:3], s[66:67], 0, v[2:3]
	v_writelane_b32 v252, s35, 40
	v_lshl_add_u64 v[136:137], s[66:67], 0, v[136:137]
	s_mov_b32 s64, 0
	s_mov_b64 s[42:43], 0x80
	v_readfirstlane_b32 vcc_lo, v216
	s_nop 3
	s_lshr_b32 vcc_lo, vcc_lo, 6
	s_cmp_ge_u32 vcc_lo, 4
	s_cbranch_scc0 .Lprio_skip4
	s_setprio 1
.Lprio_skip4:
.LBB0_913:
	s_add_i32 s35, s64, 2
	s_add_u32 s66, s62, 0x80
	s_addc_u32 s65, s63, 0
	s_add_i32 s67, 0, 0x10000
	s_add_i32 s88, 0, 0x14000
	v_add_u32_e32 v0, s67, v140
	ds_read_b128 v[144:147], v0
	ds_read_b128 v[148:151], v0 offset:1024
	ds_read_b128 v[152:155], v0 offset:2048
	ds_read_b128 v[156:159], v0 offset:3072
	v_add_u32_e32 v0, s88, v140
	s_cmp_eq_u32 s10, s64
	s_cselect_b32 s64, s60, s66
	s_cselect_b32 s65, s61, s65
	s_cselect_b32 s66, s74, s17
	s_cselect_b32 s69, s59, s15
	s_cselect_b32 s68, s58, s11
	s_cselect_b32 s89, s41, s40
	v_lshl_add_u64 v[208:209], s[62:63], 0, v[136:137]
	s_add_i32 m0, s76, 0xc000
	ds_read_b128 v[176:179], v142
	ds_read_b128 v[180:183], v142 offset:1024
	ds_read_b128 v[184:187], v142 offset:2048
	ds_read_b128 v[188:191], v142 offset:3072
	ds_read_b128 v[192:195], v142 offset:4096
	ds_read_b128 v[196:199], v142 offset:5120
	ds_read_b128 v[200:203], v142 offset:6144
	ds_read_b128 v[204:207], v142 offset:7168
	global_load_lds_dwordx4 v[208:209], off
	v_lshl_add_u64 v[208:209], s[62:63], 0, v[2:3]
	s_add_i32 m0, s76, 0xe000
	s_nop 0
	global_load_lds_dwordx4 v[208:209], off
	s_waitcnt vmcnt(6)
	s_waitcnt lgkmcnt(0)
	s_barrier
	v_mfma_f32_16x16x32_bf16 v[128:131], v[144:147], v[176:179], v[128:131]
	v_mfma_f32_16x16x32_bf16 v[124:127], v[152:155], v[176:179], v[124:127]
	v_mfma_f32_16x16x32_bf16 v[120:123], v[144:147], v[184:187], v[120:123]
	v_mfma_f32_16x16x32_bf16 v[116:119], v[152:155], v[184:187], v[116:119]
	v_mfma_f32_16x16x32_bf16 v[112:115], v[144:147], v[192:195], v[112:115]
	v_mfma_f32_16x16x32_bf16 v[108:111], v[152:155], v[192:195], v[108:111]
	v_mfma_f32_16x16x32_bf16 v[104:107], v[144:147], v[200:203], v[104:107]
	v_mfma_f32_16x16x32_bf16 v[100:103], v[152:155], v[200:203], v[100:103]
	v_mfma_f32_16x16x32_bf16 v[128:131], v[148:151], v[180:183], v[128:131]
	v_mfma_f32_16x16x32_bf16 v[124:127], v[156:159], v[180:183], v[124:127]
	v_mfma_f32_16x16x32_bf16 v[120:123], v[148:151], v[188:191], v[120:123]
	v_mfma_f32_16x16x32_bf16 v[116:119], v[156:159], v[188:191], v[116:119]
	v_mfma_f32_16x16x32_bf16 v[112:115], v[148:151], v[196:199], v[112:115]
	v_mfma_f32_16x16x32_bf16 v[108:111], v[156:159], v[196:199], v[108:111]
	v_mfma_f32_16x16x32_bf16 v[104:107], v[148:151], v[204:207], v[104:107]
	v_mfma_f32_16x16x32_bf16 v[100:103], v[156:159], v[204:207], v[100:103]
	s_barrier
	s_add_i32 s67, s67, s75
	v_mad_u64_u32 v[208:209], s[70:71], s89, v135, v[132:133]
	s_mov_b32 m0, s67
	ds_read_b128 v[176:179], v142 offset:16384
	ds_read_b128 v[180:183], v142 offset:17408
	ds_read_b128 v[184:187], v142 offset:18432
	ds_read_b128 v[188:191], v142 offset:19456
	ds_read_b128 v[192:195], v142 offset:20480
	ds_read_b128 v[196:199], v142 offset:21504
	ds_read_b128 v[200:203], v142 offset:22528
	ds_read_b128 v[204:207], v142 offset:23552
	v_mov_b32_e32 v209, v1
	global_load_lds_dwordx4 v208, s[68:69]
	v_lshl_add_u32 v0, s89, 6, v208
	s_add_i32 m0, s67, 0x2000
	s_lshl_b32 s67, s89, 7
	v_lshl_add_u64 v[210:211], s[68:69], 0, v[208:209]
	v_lshl_add_u64 v[212:213], s[68:69], 0, v[0:1]
	global_load_lds_dwordx4 v0, s[68:69]
	s_add_u32 s68, s68, s67
	s_addc_u32 s69, s69, 0
	s_add_i32 s67, s88, s75
	s_mov_b32 m0, s67
	v_lshl_add_u64 v[214:215], s[68:69], 0, v[208:209]
	s_add_i32 m0, s67, 0x2000
	v_lshl_add_u64 v[208:209], s[68:69], 0, v[0:1]
	v_mad_u64_u32 v[236:237], s[68:69], s66, v133, v[132:133]
	s_mov_b32 m0, s76
	v_lshl_add_u32 v0, s66, 6, v236
	global_load_lds_dwordx4 v236, s[64:65]
	s_mov_b32 m0, s77
	v_mov_b32_e32 v237, v1
	global_load_lds_dwordx4 v0, s[64:65]
	s_waitcnt vmcnt(6)
	s_waitcnt lgkmcnt(0)
	v_lshl_add_u64 v[238:239], s[64:65], 0, v[236:237]
	v_lshl_add_u64 v[244:245], s[64:65], 0, v[0:1]
	s_barrier
	v_mfma_f32_16x16x32_bf16 v[64:67], v[144:147], v[176:179], v[64:67]
	v_mfma_f32_16x16x32_bf16 v[60:63], v[152:155], v[176:179], v[60:63]
	v_mfma_f32_16x16x32_bf16 v[56:59], v[144:147], v[184:187], v[56:59]
	v_mfma_f32_16x16x32_bf16 v[52:55], v[152:155], v[184:187], v[52:55]
	v_mfma_f32_16x16x32_bf16 v[48:51], v[144:147], v[192:195], v[48:51]
	v_mfma_f32_16x16x32_bf16 v[44:47], v[152:155], v[192:195], v[44:47]
	v_mfma_f32_16x16x32_bf16 v[40:43], v[144:147], v[200:203], v[40:43]
	v_mfma_f32_16x16x32_bf16 v[36:39], v[152:155], v[200:203], v[36:39]
	v_mfma_f32_16x16x32_bf16 v[64:67], v[148:151], v[180:183], v[64:67]
	v_mfma_f32_16x16x32_bf16 v[60:63], v[156:159], v[180:183], v[60:63]
	v_mfma_f32_16x16x32_bf16 v[56:59], v[148:151], v[188:191], v[56:59]
	v_mfma_f32_16x16x32_bf16 v[52:55], v[156:159], v[188:191], v[52:55]
	v_mfma_f32_16x16x32_bf16 v[48:51], v[148:151], v[196:199], v[48:51]
	v_mfma_f32_16x16x32_bf16 v[44:47], v[156:159], v[196:199], v[44:47]
	v_mfma_f32_16x16x32_bf16 v[40:43], v[148:151], v[204:207], v[40:43]
	v_mfma_f32_16x16x32_bf16 v[36:39], v[156:159], v[204:207], v[36:39]
	s_barrier
	s_add_i32 s67, 0, 0x18000
	v_add_u32_e32 v143, s67, v140
	s_add_i32 s68, 0, 0x1c000
	ds_read_b128 v[144:147], v143
	ds_read_b128 v[148:151], v143 offset:1024
	ds_read_b128 v[152:155], v143 offset:2048
	ds_read_b128 v[156:159], v143 offset:3072
	v_add_u32_e32 v143, s68, v140
	s_lshl_b32 s66, s66, 7
	s_add_u32 s64, s64, s66
	s_addc_u32 s65, s65, 0
	s_mov_b32 m0, s78
	ds_read_b128 v[176:179], v142 offset:32768
	ds_read_b128 v[180:183], v142 offset:33792
	ds_read_b128 v[184:187], v142 offset:34816
	ds_read_b128 v[188:191], v142 offset:35840
	ds_read_b128 v[192:195], v142 offset:36864
	ds_read_b128 v[196:199], v142 offset:37888
	ds_read_b128 v[200:203], v142 offset:38912
	ds_read_b128 v[204:207], v142 offset:39936
	global_load_lds_dwordx4 v236, s[64:65]
	s_mov_b32 m0, s79
	s_nop 0
	global_load_lds_dwordx4 v0, s[64:65]
	s_waitcnt vmcnt(6)
	s_waitcnt lgkmcnt(0)
	s_barrier
	v_mfma_f32_16x16x32_bf16 v[128:131], v[144:147], v[176:179], v[128:131]
	v_mfma_f32_16x16x32_bf16 v[124:127], v[152:155], v[176:179], v[124:127]
	v_mfma_f32_16x16x32_bf16 v[120:123], v[144:147], v[184:187], v[120:123]
	v_mfma_f32_16x16x32_bf16 v[116:119], v[152:155], v[184:187], v[116:119]
	v_mfma_f32_16x16x32_bf16 v[112:115], v[144:147], v[192:195], v[112:115]
	v_mfma_f32_16x16x32_bf16 v[108:111], v[152:155], v[192:195], v[108:111]
	v_mfma_f32_16x16x32_bf16 v[104:107], v[144:147], v[200:203], v[104:107]
	v_mfma_f32_16x16x32_bf16 v[100:103], v[152:155], v[200:203], v[100:103]
	v_mfma_f32_16x16x32_bf16 v[128:131], v[148:151], v[180:183], v[128:131]
	v_mfma_f32_16x16x32_bf16 v[124:127], v[156:159], v[180:183], v[124:127]
	v_mfma_f32_16x16x32_bf16 v[120:123], v[148:151], v[188:191], v[120:123]
	v_mfma_f32_16x16x32_bf16 v[116:119], v[156:159], v[188:191], v[116:119]
	v_mfma_f32_16x16x32_bf16 v[112:115], v[148:151], v[196:199], v[112:115]
	v_mfma_f32_16x16x32_bf16 v[108:111], v[156:159], v[196:199], v[108:111]
	v_mfma_f32_16x16x32_bf16 v[104:107], v[148:151], v[204:207], v[104:107]
	v_mfma_f32_16x16x32_bf16 v[100:103], v[156:159], v[204:207], v[100:103]
	s_barrier
	s_add_i32 s64, s67, s75
	v_lshl_add_u64 v[210:211], v[210:211], 0, s[42:43]
	s_mov_b32 m0, s64
	ds_read_b128 v[176:179], v142 offset:49152
	ds_read_b128 v[180:183], v142 offset:50176
	ds_read_b128 v[184:187], v142 offset:51200
	ds_read_b128 v[188:191], v142 offset:52224
	ds_read_b128 v[192:195], v142 offset:53248
	ds_read_b128 v[196:199], v142 offset:54272
	ds_read_b128 v[200:203], v142 offset:55296
	ds_read_b128 v[204:207], v142 offset:56320
	global_load_lds_dwordx4 v[210:211], off
	v_lshl_add_u64 v[210:211], v[212:213], 0, s[42:43]
	s_add_i32 m0, s64, 0x2000
	s_add_i32 s64, s68, s75
	global_load_lds_dwordx4 v[210:211], off
	v_lshl_add_u64 v[210:211], v[214:215], 0, s[42:43]
	s_mov_b32 m0, s64
	v_lshl_add_u64 v[208:209], v[208:209], 0, s[42:43]
	s_add_i32 m0, s64, 0x2000
	s_nop 0
	v_lshl_add_u64 v[208:209], v[238:239], 0, s[42:43]
	s_mov_b32 m0, s82
	s_nop 0
	global_load_lds_dwordx4 v[208:209], off
	v_lshl_add_u64 v[208:209], v[244:245], 0, s[42:43]
	s_mov_b32 m0, s83
	s_nop 0
	global_load_lds_dwordx4 v[208:209], off
	s_waitcnt vmcnt(6)
	s_waitcnt lgkmcnt(0)
	s_barrier
	v_mfma_f32_16x16x32_bf16 v[64:67], v[144:147], v[176:179], v[64:67]
	v_mfma_f32_16x16x32_bf16 v[60:63], v[152:155], v[176:179], v[60:63]
	v_mfma_f32_16x16x32_bf16 v[56:59], v[144:147], v[184:187], v[56:59]
	v_mfma_f32_16x16x32_bf16 v[52:55], v[152:155], v[184:187], v[52:55]
	v_mfma_f32_16x16x32_bf16 v[48:51], v[144:147], v[192:195], v[48:51]
	v_mfma_f32_16x16x32_bf16 v[44:47], v[152:155], v[192:195], v[44:47]
	v_mfma_f32_16x16x32_bf16 v[40:43], v[144:147], v[200:203], v[40:43]
	v_mfma_f32_16x16x32_bf16 v[36:39], v[152:155], v[200:203], v[36:39]
	v_mfma_f32_16x16x32_bf16 v[64:67], v[148:151], v[180:183], v[64:67]
	v_mfma_f32_16x16x32_bf16 v[60:63], v[156:159], v[180:183], v[60:63]
	v_mfma_f32_16x16x32_bf16 v[56:59], v[148:151], v[188:191], v[56:59]
	v_mfma_f32_16x16x32_bf16 v[52:55], v[156:159], v[188:191], v[52:55]
	v_mfma_f32_16x16x32_bf16 v[48:51], v[148:151], v[196:199], v[48:51]
	v_mfma_f32_16x16x32_bf16 v[44:47], v[156:159], v[196:199], v[44:47]
	v_mfma_f32_16x16x32_bf16 v[40:43], v[148:151], v[204:207], v[40:43]
	v_mfma_f32_16x16x32_bf16 v[36:39], v[156:159], v[204:207], v[36:39]
	s_barrier
	s_add_u32 s11, s11, 0x100
	s_addc_u32 s15, s15, 0
	s_add_u32 s62, s62, 0x100
	s_addc_u32 s63, s63, 0
	s_cmp_ge_i32 s35, s44
	s_mov_b32 s64, s35
	s_cbranch_scc0 .LBB0_913
	s_setprio 0

.LBB0_1025:
	s_add_u32 s74, s0, 0x100
	s_addc_u32 s75, s1, 0
	s_add_u32 s0, s14, 0x40080
	s_addc_u32 s1, s15, 0
	v_lshl_add_u64 v[130:131], s[0:1], 0, v[146:147]
	v_lshl_add_u64 v[132:133], s[0:1], 0, v[144:145]
	s_mov_b32 s6, -2
	s_mov_b64 s[0:1], 0
	s_mov_b64 s[42:43], 0x80
	v_readfirstlane_b32 vcc_lo, v216
	s_nop 3
	s_lshr_b32 vcc_lo, vcc_lo, 6
	s_cmp_ge_u32 vcc_lo, 4
	s_cbranch_scc0 .Lprio_skip0
	s_setprio 1
.Lprio_skip0:
.LBB0_1026:
	s_add_u32 s2, s14, s0
	s_addc_u32 s3, s15, s1
	s_add_u32 s2, s2, 0x100
	s_addc_u32 s3, s3, 0
	s_add_u32 s7, s74, s0
	s_addc_u32 s37, s75, s1
	s_add_i32 s80, 0, 0x10000
	s_add_i32 s81, 0, 0x14000
	v_add_u32_e32 v0, s80, v180
	ds_read_b128 v[134:137], v0
	ds_read_b128 v[148:151], v0 offset:1024
	ds_read_b128 v[152:155], v0 offset:2048
	ds_read_b128 v[156:159], v0 offset:3072
	v_add_u32_e32 v0, s81, v180
	ds_read_b128 v[160:163], v0
	ds_read_b128 v[164:167], v0 offset:1024
	ds_read_b128 v[168:171], v0 offset:2048
	ds_read_b128 v[172:175], v0 offset:3072
	s_cmpk_eq_i32 s0, 0x700
	s_cselect_b32 s3, s47, s3
	s_cselect_b32 s2, s46, s2
	s_cselect_b32 s77, s39, s37
	s_cselect_b32 s76, s38, s7
	s_cselect_b32 s7, s73, s50
	v_lshl_add_u64 v[176:177], v[132:133], 0, s[0:1]
	s_add_i32 m0, s49, 0xc000
	ds_read_b128 v[182:185], v181
	ds_read_b128 v[186:189], v181 offset:1024
	ds_read_b128 v[190:193], v181 offset:2048
	ds_read_b128 v[194:197], v181 offset:3072
	ds_read_b128 v[198:201], v181 offset:4096
	ds_read_b128 v[202:205], v181 offset:5120
	ds_read_b128 v[206:209], v181 offset:6144
	ds_read_b128 v[210:213], v181 offset:7168
	global_load_lds_dwordx4 v[176:177], off
	v_lshl_add_u64 v[176:177], v[130:131], 0, s[0:1]
	s_add_i32 m0, s49, 0xe000
	s_nop 0
	global_load_lds_dwordx4 v[176:177], off
	s_waitcnt vmcnt(8)
	s_waitcnt lgkmcnt(0)
	s_barrier
	v_mfma_f32_16x16x32_bf16 v[126:129], v[134:137], v[182:185], v[126:129]
	v_mfma_f32_16x16x32_bf16 v[122:125], v[152:155], v[182:185], v[122:125]
	v_mfma_f32_16x16x32_bf16 v[118:121], v[134:137], v[190:193], v[118:121]
	v_mfma_f32_16x16x32_bf16 v[114:117], v[152:155], v[190:193], v[114:117]
	v_mfma_f32_16x16x32_bf16 v[110:113], v[134:137], v[198:201], v[110:113]
	v_mfma_f32_16x16x32_bf16 v[106:109], v[152:155], v[198:201], v[106:109]
	v_mfma_f32_16x16x32_bf16 v[102:105], v[134:137], v[206:209], v[102:105]
	v_mfma_f32_16x16x32_bf16 v[98:101], v[152:155], v[206:209], v[98:101]
	v_mfma_f32_16x16x32_bf16 v[126:129], v[148:151], v[186:189], v[126:129]
	v_mfma_f32_16x16x32_bf16 v[122:125], v[156:159], v[186:189], v[122:125]
	v_mfma_f32_16x16x32_bf16 v[118:121], v[148:151], v[194:197], v[118:121]
	v_mfma_f32_16x16x32_bf16 v[114:117], v[156:159], v[194:197], v[114:117]
	v_mfma_f32_16x16x32_bf16 v[110:113], v[148:151], v[202:205], v[110:113]
	v_mfma_f32_16x16x32_bf16 v[106:109], v[156:159], v[202:205], v[106:109]
	v_mfma_f32_16x16x32_bf16 v[102:105], v[148:151], v[210:213], v[102:105]
	v_mfma_f32_16x16x32_bf16 v[98:101], v[156:159], v[210:213], v[98:101]
	v_mfma_f32_16x16x32_bf16 v[94:97], v[160:163], v[182:185], v[94:97]
	v_mfma_f32_16x16x32_bf16 v[90:93], v[168:171], v[182:185], v[90:93]
	v_mfma_f32_16x16x32_bf16 v[86:89], v[160:163], v[190:193], v[86:89]
	v_mfma_f32_16x16x32_bf16 v[82:85], v[168:171], v[190:193], v[82:85]
	v_mfma_f32_16x16x32_bf16 v[78:81], v[160:163], v[198:201], v[78:81]
	v_mfma_f32_16x16x32_bf16 v[74:77], v[168:171], v[198:201], v[74:77]
	v_mfma_f32_16x16x32_bf16 v[70:73], v[160:163], v[206:209], v[70:73]
	v_mfma_f32_16x16x32_bf16 v[66:69], v[168:171], v[206:209], v[66:69]
	v_mfma_f32_16x16x32_bf16 v[94:97], v[164:167], v[186:189], v[94:97]
	v_mfma_f32_16x16x32_bf16 v[90:93], v[172:175], v[186:189], v[90:93]
	v_mfma_f32_16x16x32_bf16 v[86:89], v[164:167], v[194:197], v[86:89]
	v_mfma_f32_16x16x32_bf16 v[82:85], v[172:175], v[194:197], v[82:85]
	v_mfma_f32_16x16x32_bf16 v[78:81], v[164:167], v[202:205], v[78:81]
	v_mfma_f32_16x16x32_bf16 v[74:77], v[172:175], v[202:205], v[74:77]
	v_mfma_f32_16x16x32_bf16 v[70:73], v[164:167], v[210:213], v[70:73]
	v_mfma_f32_16x16x32_bf16 v[66:69], v[172:175], v[210:213], v[66:69]
	s_barrier
	s_add_i32 s37, s80, s48
	v_mad_u64_u32 v[176:177], s[78:79], s7, v139, v[138:139]
	s_mov_b32 m0, s37
	ds_read_b128 v[182:185], v181 offset:16384
	ds_read_b128 v[186:189], v181 offset:17408
	ds_read_b128 v[190:193], v181 offset:18432
	ds_read_b128 v[194:197], v181 offset:19456
	ds_read_b128 v[198:201], v181 offset:20480
	ds_read_b128 v[202:205], v181 offset:21504
	ds_read_b128 v[206:209], v181 offset:22528
	ds_read_b128 v[210:213], v181 offset:23552
	v_mov_b32_e32 v177, v1
	global_load_lds_dwordx4 v176, s[76:77]
	v_lshl_add_u32 v0, s7, 6, v176
	s_add_i32 m0, s37, 0x2000
	s_lshl_b32 s7, s7, 7
	v_lshl_add_u64 v[214:215], s[76:77], 0, v[176:177]
	v_lshl_add_u64 v[236:237], s[76:77], 0, v[0:1]
	global_load_lds_dwordx4 v0, s[76:77]
	s_add_u32 s76, s76, s7
	s_addc_u32 s77, s77, 0
	s_add_i32 s7, s81, s48
	s_mov_b32 m0, s7
	v_lshl_add_u64 v[246:247], s[2:3], 0, v[140:141]
	global_load_lds_dwordx4 v176, s[76:77]
	s_add_i32 m0, s7, 0x2000
	v_lshl_add_u64 v[248:249], s[2:3], 0, v[142:143]
	global_load_lds_dwordx4 v0, s[76:77]
	s_mov_b32 m0, s49
	v_lshl_add_u64 v[238:239], s[76:77], 0, v[176:177]
	global_load_lds_dwordx4 v[246:247], off
	s_mov_b32 m0, s51
	v_lshl_add_u64 v[176:177], s[76:77], 0, v[0:1]
	global_load_lds_dwordx4 v[248:249], off
	s_waitcnt vmcnt(8)
	s_waitcnt lgkmcnt(0)
	s_barrier
	v_mfma_f32_16x16x32_bf16 v[62:65], v[134:137], v[182:185], v[62:65]
	v_mfma_f32_16x16x32_bf16 v[58:61], v[152:155], v[182:185], v[58:61]
	v_mfma_f32_16x16x32_bf16 v[54:57], v[134:137], v[190:193], v[54:57]
	v_mfma_f32_16x16x32_bf16 v[50:53], v[152:155], v[190:193], v[50:53]
	v_mfma_f32_16x16x32_bf16 v[46:49], v[134:137], v[198:201], v[46:49]
	v_mfma_f32_16x16x32_bf16 v[42:45], v[152:155], v[198:201], v[42:45]
	v_mfma_f32_16x16x32_bf16 v[38:41], v[134:137], v[206:209], v[38:41]
	v_mfma_f32_16x16x32_bf16 v[34:37], v[152:155], v[206:209], v[34:37]
	v_mfma_f32_16x16x32_bf16 v[62:65], v[148:151], v[186:189], v[62:65]
	v_mfma_f32_16x16x32_bf16 v[58:61], v[156:159], v[186:189], v[58:61]
	v_mfma_f32_16x16x32_bf16 v[54:57], v[148:151], v[194:197], v[54:57]
	v_mfma_f32_16x16x32_bf16 v[50:53], v[156:159], v[194:197], v[50:53]
	v_mfma_f32_16x16x32_bf16 v[46:49], v[148:151], v[202:205], v[46:49]
	v_mfma_f32_16x16x32_bf16 v[42:45], v[156:159], v[202:205], v[42:45]
	v_mfma_f32_16x16x32_bf16 v[38:41], v[148:151], v[210:213], v[38:41]
	v_mfma_f32_16x16x32_bf16 v[34:37], v[156:159], v[210:213], v[34:37]
	v_mfma_f32_16x16x32_bf16 v[30:33], v[160:163], v[182:185], v[30:33]
	v_mfma_f32_16x16x32_bf16 v[26:29], v[168:171], v[182:185], v[26:29]
	v_mfma_f32_16x16x32_bf16 v[22:25], v[160:163], v[190:193], v[22:25]
	v_mfma_f32_16x16x32_bf16 v[18:21], v[168:171], v[190:193], v[18:21]
	v_mfma_f32_16x16x32_bf16 v[14:17], v[160:163], v[198:201], v[14:17]
	v_mfma_f32_16x16x32_bf16 v[10:13], v[168:171], v[198:201], v[10:13]
	v_mfma_f32_16x16x32_bf16 v[6:9], v[160:163], v[206:209], v[6:9]
	v_mfma_f32_16x16x32_bf16 v[2:5], v[168:171], v[206:209], v[2:5]
	v_mfma_f32_16x16x32_bf16 v[30:33], v[164:167], v[186:189], v[30:33]
	v_mfma_f32_16x16x32_bf16 v[26:29], v[172:175], v[186:189], v[26:29]
	v_mfma_f32_16x16x32_bf16 v[22:25], v[164:167], v[194:197], v[22:25]
	v_mfma_f32_16x16x32_bf16 v[18:21], v[172:175], v[194:197], v[18:21]
	v_mfma_f32_16x16x32_bf16 v[14:17], v[164:167], v[202:205], v[14:17]
	v_mfma_f32_16x16x32_bf16 v[10:13], v[172:175], v[202:205], v[10:13]
	v_mfma_f32_16x16x32_bf16 v[6:9], v[164:167], v[210:213], v[6:9]
	v_mfma_f32_16x16x32_bf16 v[2:5], v[172:175], v[210:213], v[2:5]
	s_barrier
	s_add_i32 s7, 0, 0x18000
	v_add_u32_e32 v0, s7, v180
	s_add_i32 s37, 0, 0x1c000
	ds_read_b128 v[134:137], v0
	ds_read_b128 v[148:151], v0 offset:1024
	ds_read_b128 v[152:155], v0 offset:2048
	ds_read_b128 v[156:159], v0 offset:3072
	v_add_u32_e32 v0, s37, v180
	ds_read_b128 v[160:163], v0
	ds_read_b128 v[164:167], v0 offset:1024
	ds_read_b128 v[168:171], v0 offset:2048
	ds_read_b128 v[172:175], v0 offset:3072
	s_add_u32 s2, s2, 0x40000
	s_addc_u32 s3, s3, 0
	s_mov_b32 m0, s52
	v_lshl_add_u64 v[244:245], s[2:3], 0, v[140:141]
	ds_read_b128 v[182:185], v181 offset:32768
	ds_read_b128 v[186:189], v181 offset:33792
	ds_read_b128 v[190:193], v181 offset:34816
	ds_read_b128 v[194:197], v181 offset:35840
	ds_read_b128 v[198:201], v181 offset:36864
	ds_read_b128 v[202:205], v181 offset:37888
	ds_read_b128 v[206:209], v181 offset:38912
	ds_read_b128 v[210:213], v181 offset:39936
	global_load_lds_dwordx4 v[244:245], off
	v_lshl_add_u64 v[244:245], s[2:3], 0, v[142:143]
	s_mov_b32 m0, s53
	s_nop 0
	global_load_lds_dwordx4 v[244:245], off
	s_waitcnt vmcnt(8)
	s_waitcnt lgkmcnt(0)
	s_barrier
	v_mfma_f32_16x16x32_bf16 v[126:129], v[134:137], v[182:185], v[126:129]
	v_mfma_f32_16x16x32_bf16 v[122:125], v[152:155], v[182:185], v[122:125]
	v_mfma_f32_16x16x32_bf16 v[118:121], v[134:137], v[190:193], v[118:121]
	v_mfma_f32_16x16x32_bf16 v[114:117], v[152:155], v[190:193], v[114:117]
	v_mfma_f32_16x16x32_bf16 v[110:113], v[134:137], v[198:201], v[110:113]
	v_mfma_f32_16x16x32_bf16 v[106:109], v[152:155], v[198:201], v[106:109]
	v_mfma_f32_16x16x32_bf16 v[102:105], v[134:137], v[206:209], v[102:105]
	v_mfma_f32_16x16x32_bf16 v[98:101], v[152:155], v[206:209], v[98:101]
	v_mfma_f32_16x16x32_bf16 v[126:129], v[148:151], v[186:189], v[126:129]
	v_mfma_f32_16x16x32_bf16 v[122:125], v[156:159], v[186:189], v[122:125]
	v_mfma_f32_16x16x32_bf16 v[118:121], v[148:151], v[194:197], v[118:121]
	v_mfma_f32_16x16x32_bf16 v[114:117], v[156:159], v[194:197], v[114:117]
	v_mfma_f32_16x16x32_bf16 v[110:113], v[148:151], v[202:205], v[110:113]
	v_mfma_f32_16x16x32_bf16 v[106:109], v[156:159], v[202:205], v[106:109]
	v_mfma_f32_16x16x32_bf16 v[102:105], v[148:151], v[210:213], v[102:105]
	v_mfma_f32_16x16x32_bf16 v[98:101], v[156:159], v[210:213], v[98:101]
	v_mfma_f32_16x16x32_bf16 v[94:97], v[160:163], v[182:185], v[94:97]
	v_mfma_f32_16x16x32_bf16 v[90:93], v[168:171], v[182:185], v[90:93]
	v_mfma_f32_16x16x32_bf16 v[86:89], v[160:163], v[190:193], v[86:89]
	v_mfma_f32_16x16x32_bf16 v[82:85], v[168:171], v[190:193], v[82:85]
	v_mfma_f32_16x16x32_bf16 v[78:81], v[160:163], v[198:201], v[78:81]
	v_mfma_f32_16x16x32_bf16 v[74:77], v[168:171], v[198:201], v[74:77]
	v_mfma_f32_16x16x32_bf16 v[70:73], v[160:163], v[206:209], v[70:73]
	v_mfma_f32_16x16x32_bf16 v[66:69], v[168:171], v[206:209], v[66:69]
	v_mfma_f32_16x16x32_bf16 v[94:97], v[164:167], v[186:189], v[94:97]
	v_mfma_f32_16x16x32_bf16 v[90:93], v[172:175], v[186:189], v[90:93]
	v_mfma_f32_16x16x32_bf16 v[86:89], v[164:167], v[194:197], v[86:89]
	v_mfma_f32_16x16x32_bf16 v[82:85], v[172:175], v[194:197], v[82:85]
	v_mfma_f32_16x16x32_bf16 v[78:81], v[164:167], v[202:205], v[78:81]
	v_mfma_f32_16x16x32_bf16 v[74:77], v[172:175], v[202:205], v[74:77]
	v_mfma_f32_16x16x32_bf16 v[70:73], v[164:167], v[210:213], v[70:73]
	v_mfma_f32_16x16x32_bf16 v[66:69], v[172:175], v[210:213], v[66:69]
	s_barrier
	s_add_i32 s2, s7, s48
	v_lshl_add_u64 v[214:215], v[214:215], 0, s[42:43]
	s_mov_b32 m0, s2
	ds_read_b128 v[182:185], v181 offset:49152
	ds_read_b128 v[186:189], v181 offset:50176
	ds_read_b128 v[190:193], v181 offset:51200
	ds_read_b128 v[194:197], v181 offset:52224
	ds_read_b128 v[198:201], v181 offset:53248
	ds_read_b128 v[202:205], v181 offset:54272
	ds_read_b128 v[206:209], v181 offset:55296
	ds_read_b128 v[210:213], v181 offset:56320
	global_load_lds_dwordx4 v[214:215], off
	v_lshl_add_u64 v[214:215], v[236:237], 0, s[42:43]
	s_add_i32 m0, s2, 0x2000
	s_add_i32 s2, s37, s48
	global_load_lds_dwordx4 v[214:215], off
	v_lshl_add_u64 v[214:215], v[238:239], 0, s[42:43]
	s_mov_b32 m0, s2
	v_lshl_add_u64 v[176:177], v[176:177], 0, s[42:43]
	global_load_lds_dwordx4 v[214:215], off
	s_add_i32 m0, s2, 0x2000
	s_nop 0
	global_load_lds_dwordx4 v[176:177], off
	v_lshl_add_u64 v[176:177], v[246:247], 0, s[42:43]
	s_mov_b32 m0, s56
	s_nop 0
	global_load_lds_dwordx4 v[176:177], off
	v_lshl_add_u64 v[176:177], v[248:249], 0, s[42:43]
	s_mov_b32 m0, s57
	s_nop 0
	global_load_lds_dwordx4 v[176:177], off
	s_waitcnt vmcnt(8)
	s_waitcnt lgkmcnt(0)
	s_barrier
	v_mfma_f32_16x16x32_bf16 v[62:65], v[134:137], v[182:185], v[62:65]
	v_mfma_f32_16x16x32_bf16 v[58:61], v[152:155], v[182:185], v[58:61]
	v_mfma_f32_16x16x32_bf16 v[54:57], v[134:137], v[190:193], v[54:57]
	v_mfma_f32_16x16x32_bf16 v[50:53], v[152:155], v[190:193], v[50:53]
	v_mfma_f32_16x16x32_bf16 v[46:49], v[134:137], v[198:201], v[46:49]
	v_mfma_f32_16x16x32_bf16 v[42:45], v[152:155], v[198:201], v[42:45]
	v_mfma_f32_16x16x32_bf16 v[38:41], v[134:137], v[206:209], v[38:41]
	v_mfma_f32_16x16x32_bf16 v[34:37], v[152:155], v[206:209], v[34:37]
	v_mfma_f32_16x16x32_bf16 v[62:65], v[148:151], v[186:189], v[62:65]
	v_mfma_f32_16x16x32_bf16 v[58:61], v[156:159], v[186:189], v[58:61]
	v_mfma_f32_16x16x32_bf16 v[54:57], v[148:151], v[194:197], v[54:57]
	v_mfma_f32_16x16x32_bf16 v[50:53], v[156:159], v[194:197], v[50:53]
	v_mfma_f32_16x16x32_bf16 v[46:49], v[148:151], v[202:205], v[46:49]
	v_mfma_f32_16x16x32_bf16 v[42:45], v[156:159], v[202:205], v[42:45]
	v_mfma_f32_16x16x32_bf16 v[38:41], v[148:151], v[210:213], v[38:41]
	v_mfma_f32_16x16x32_bf16 v[34:37], v[156:159], v[210:213], v[34:37]
	v_mfma_f32_16x16x32_bf16 v[30:33], v[160:163], v[182:185], v[30:33]
	v_mfma_f32_16x16x32_bf16 v[26:29], v[168:171], v[182:185], v[26:29]
	v_mfma_f32_16x16x32_bf16 v[22:25], v[160:163], v[190:193], v[22:25]
	v_mfma_f32_16x16x32_bf16 v[18:21], v[168:171], v[190:193], v[18:21]
	v_mfma_f32_16x16x32_bf16 v[14:17], v[160:163], v[198:201], v[14:17]
	v_mfma_f32_16x16x32_bf16 v[10:13], v[168:171], v[198:201], v[10:13]
	v_mfma_f32_16x16x32_bf16 v[6:9], v[160:163], v[206:209], v[6:9]
	v_mfma_f32_16x16x32_bf16 v[2:5], v[168:171], v[206:209], v[2:5]
	v_mfma_f32_16x16x32_bf16 v[30:33], v[164:167], v[186:189], v[30:33]
	v_mfma_f32_16x16x32_bf16 v[26:29], v[172:175], v[186:189], v[26:29]
	v_mfma_f32_16x16x32_bf16 v[22:25], v[164:167], v[194:197], v[22:25]
	v_mfma_f32_16x16x32_bf16 v[18:21], v[172:175], v[194:197], v[18:21]
	v_mfma_f32_16x16x32_bf16 v[14:17], v[164:167], v[202:205], v[14:17]
	v_mfma_f32_16x16x32_bf16 v[10:13], v[172:175], v[202:205], v[10:13]
	v_mfma_f32_16x16x32_bf16 v[6:9], v[164:167], v[210:213], v[6:9]
	v_mfma_f32_16x16x32_bf16 v[2:5], v[172:175], v[210:213], v[2:5]
	s_barrier
	s_add_i32 s6, s6, 2
	s_add_u32 s0, s0, 0x100
	s_addc_u32 s1, s1, 0
	s_cmp_gt_u32 s6, 13
	s_cbranch_scc0 .LBB0_1026
	s_setprio 0
	s_and_b64 vcc, exec, s[18:19]
	s_cbranch_vccz .LBB0_1029
	s_barrier
